# GEMM K-loops: priority raised during the LDS-read/DMA blocks (half of them) instead of the MFMA blocks
# baseline (speedup 1.0000x reference)
.LBB0_70:
	s_add_i32 s35, s18, 2
	s_add_u32 s16, s12, 0x100
	s_addc_u32 s17, s13, 0
	s_cmp_lg_u32 s34, s18
	s_cselect_b32 s22, s16, 0
	s_cselect_b32 s23, s17, 0
	s_add_u32 s18, s10, s22
	s_addc_u32 s19, s11, s23
	s_add_i32 s36, 0, 0x10000
	s_add_u32 s22, s8, s22
	s_addc_u32 s23, s9, s23
	v_lshl_add_u64 v[190:191], v[130:131], 0, s[12:13]
	s_add_i32 m0, s3, 0xc000
	ds_read_b128 v[170:173], v153
	ds_read_b128 v[178:181], v153 offset:2048
	ds_read_b128 v[186:189], v153 offset:4096
	ds_read_b128 v[220:223], v153 offset:6144
	ds_read_b128 v[174:177], v153 offset:1024
	ds_read_b128 v[182:185], v153 offset:3072
	ds_read_b128 v[216:219], v153 offset:5120
	ds_read_b128 v[224:227], v153 offset:7168
	global_load_lds_dwordx4 v[190:191], off
	v_lshl_add_u64 v[190:191], v[150:151], 0, s[12:13]
	s_add_i32 m0, s3, 0xe000
	s_nop 0
	global_load_lds_dwordx4 v[190:191], off
	s_waitcnt lgkmcnt(8)
	s_setprio 0
	s_waitcnt vmcnt(10)
	s_barrier
	s_waitcnt lgkmcnt(4)
	v_mfma_f32_16x16x32_bf16 v[124:127], v[154:157], v[170:173], v[124:127]
	v_mfma_f32_16x16x32_bf16 v[120:123], v[162:165], v[170:173], v[120:123]
	v_mfma_f32_16x16x32_bf16 v[116:119], v[154:157], v[178:181], v[116:119]
	v_mfma_f32_16x16x32_bf16 v[108:111], v[162:165], v[178:181], v[108:111]
	v_mfma_f32_16x16x32_bf16 v[100:103], v[154:157], v[186:189], v[100:103]
	v_mfma_f32_16x16x32_bf16 v[92:95], v[162:165], v[186:189], v[92:95]
	v_mfma_f32_16x16x32_bf16 v[84:87], v[154:157], v[220:223], v[84:87]
	v_mfma_f32_16x16x32_bf16 v[76:79], v[162:165], v[220:223], v[76:79]
	s_waitcnt lgkmcnt(0)
	v_mfma_f32_16x16x32_bf16 v[124:127], v[158:161], v[174:177], v[124:127]
	v_mfma_f32_16x16x32_bf16 v[120:123], v[166:169], v[174:177], v[120:123]
	v_mfma_f32_16x16x32_bf16 v[116:119], v[158:161], v[182:185], v[116:119]
	v_mfma_f32_16x16x32_bf16 v[108:111], v[166:169], v[182:185], v[108:111]
	v_mfma_f32_16x16x32_bf16 v[100:103], v[158:161], v[216:219], v[100:103]
	v_mfma_f32_16x16x32_bf16 v[92:95], v[166:169], v[216:219], v[92:95]
	v_mfma_f32_16x16x32_bf16 v[84:87], v[158:161], v[224:227], v[84:87]
	v_mfma_f32_16x16x32_bf16 v[76:79], v[166:169], v[224:227], v[76:79]
	s_barrier
	s_setprio 1
	s_add_i32 s37, 0, 0x14000
	v_add_u32_e32 v190, s37, v152
	s_add_i32 s12, s36, s26
	ds_read_b128 v[228:231], v190
	ds_read_b128 v[236:239], v190 offset:2048
	ds_read_b128 v[232:235], v190 offset:1024
	ds_read_b128 v[240:243], v190 offset:3072
	v_lshl_add_u64 v[190:191], s[22:23], 0, v[132:133]
	s_mov_b32 m0, s12
	v_lshl_add_u64 v[244:245], s[22:23], 0, v[128:129]
	global_load_lds_dwordx4 v132, s[22:23]
	s_add_i32 m0, s12, 0x2000
	s_nop 0
	global_load_lds_dwordx4 v128, s[22:23]
	s_setprio 0
	s_waitcnt vmcnt(10)
	s_barrier
	s_waitcnt lgkmcnt(2)
	v_mfma_f32_16x16x32_bf16 v[112:115], v[228:231], v[170:173], v[112:115]
	v_mfma_f32_16x16x32_bf16 v[104:107], v[236:239], v[170:173], v[104:107]
	v_mfma_f32_16x16x32_bf16 v[96:99], v[228:231], v[178:181], v[96:99]
	v_mfma_f32_16x16x32_bf16 v[88:91], v[236:239], v[178:181], v[88:91]
	v_mfma_f32_16x16x32_bf16 v[80:83], v[228:231], v[186:189], v[80:83]
	v_mfma_f32_16x16x32_bf16 v[72:75], v[236:239], v[186:189], v[72:75]
	v_mfma_f32_16x16x32_bf16 v[68:71], v[228:231], v[220:223], v[68:71]
	v_mfma_f32_16x16x32_bf16 v[64:67], v[236:239], v[220:223], v[64:67]
	s_waitcnt lgkmcnt(0)
	v_mfma_f32_16x16x32_bf16 v[112:115], v[232:235], v[174:177], v[112:115]
	v_mfma_f32_16x16x32_bf16 v[104:107], v[240:243], v[174:177], v[104:107]
	v_mfma_f32_16x16x32_bf16 v[96:99], v[232:235], v[182:185], v[96:99]
	v_mfma_f32_16x16x32_bf16 v[88:91], v[240:243], v[182:185], v[88:91]
	v_mfma_f32_16x16x32_bf16 v[80:83], v[232:235], v[216:219], v[80:83]
	v_mfma_f32_16x16x32_bf16 v[72:75], v[240:243], v[216:219], v[72:75]
	v_mfma_f32_16x16x32_bf16 v[68:71], v[232:235], v[224:227], v[68:71]
	v_mfma_f32_16x16x32_bf16 v[64:67], v[240:243], v[224:227], v[64:67]
	s_mov_b32 m0, s3
	s_barrier
	ds_read_b128 v[170:173], v153 offset:16384
	ds_read_b128 v[178:181], v153 offset:18432
	ds_read_b128 v[186:189], v153 offset:20480
	ds_read_b128 v[220:223], v153 offset:22528
	ds_read_b128 v[174:177], v153 offset:17408
	ds_read_b128 v[182:185], v153 offset:19456
	ds_read_b128 v[216:219], v153 offset:21504
	ds_read_b128 v[224:227], v153 offset:23552
	global_load_lds_dwordx4 v132, s[18:19]
	s_mov_b32 m0, s5
	s_nop 0
	global_load_lds_dwordx4 v128, s[18:19]
	s_setprio 0
	s_waitcnt vmcnt(10)
	s_barrier
	s_waitcnt lgkmcnt(4)
	v_mfma_f32_16x16x32_bf16 v[60:63], v[154:157], v[170:173], v[60:63]
	v_mfma_f32_16x16x32_bf16 v[56:59], v[162:165], v[170:173], v[56:59]
	v_mfma_f32_16x16x32_bf16 v[52:55], v[154:157], v[178:181], v[52:55]
	v_mfma_f32_16x16x32_bf16 v[44:47], v[162:165], v[178:181], v[44:47]
	v_mfma_f32_16x16x32_bf16 v[36:39], v[154:157], v[186:189], v[36:39]
	v_mfma_f32_16x16x32_bf16 v[28:31], v[162:165], v[186:189], v[28:31]
	v_mfma_f32_16x16x32_bf16 v[20:23], v[154:157], v[220:223], v[20:23]
	v_mfma_f32_16x16x32_bf16 v[12:15], v[162:165], v[220:223], v[12:15]
	s_waitcnt lgkmcnt(0)
	v_mfma_f32_16x16x32_bf16 v[60:63], v[158:161], v[174:177], v[60:63]
	v_mfma_f32_16x16x32_bf16 v[56:59], v[166:169], v[174:177], v[56:59]
	v_mfma_f32_16x16x32_bf16 v[52:55], v[158:161], v[182:185], v[52:55]
	v_mfma_f32_16x16x32_bf16 v[44:47], v[166:169], v[182:185], v[44:47]
	v_mfma_f32_16x16x32_bf16 v[36:39], v[158:161], v[216:219], v[36:39]
	v_mfma_f32_16x16x32_bf16 v[28:31], v[166:169], v[216:219], v[28:31]
	v_mfma_f32_16x16x32_bf16 v[20:23], v[158:161], v[224:227], v[20:23]
	v_mfma_f32_16x16x32_bf16 v[12:15], v[166:169], v[224:227], v[12:15]
	s_barrier
	s_setprio 1
	s_add_u32 s12, s22, s25
	s_addc_u32 s13, s23, 0
	s_add_i32 s22, s37, s26
	v_lshl_add_u64 v[250:251], s[12:13], 0, v[132:133]
	s_mov_b32 m0, s22
	v_lshl_add_u64 v[252:253], s[12:13], 0, v[128:129]
	global_load_lds_dwordx4 v132, s[12:13]
	s_add_i32 m0, s22, 0x2000
	s_nop 0
	global_load_lds_dwordx4 v128, s[12:13]
	v_add_u32_e32 v166, 0x18000, v152
	ds_read_b128 v[154:157], v166
	ds_read_b128 v[158:161], v166 offset:1024
	ds_read_b128 v[162:165], v166 offset:2048
	ds_read_b128 v[166:169], v166 offset:3072
	s_setprio 0
	s_waitcnt vmcnt(10)
	s_barrier
	v_mfma_f32_16x16x32_bf16 v[48:51], v[228:231], v[170:173], v[48:51]
	v_mfma_f32_16x16x32_bf16 v[40:43], v[236:239], v[170:173], v[40:43]
	v_mfma_f32_16x16x32_bf16 v[32:35], v[228:231], v[178:181], v[32:35]
	v_mfma_f32_16x16x32_bf16 v[24:27], v[236:239], v[178:181], v[24:27]
	v_mfma_f32_16x16x32_bf16 v[16:19], v[228:231], v[186:189], v[16:19]
	v_mfma_f32_16x16x32_bf16 v[8:11], v[236:239], v[186:189], v[8:11]
	v_mfma_f32_16x16x32_bf16 v[4:7], v[228:231], v[220:223], v[4:7]
	v_mfma_f32_16x16x32_bf16 v[0:3], v[236:239], v[220:223], v[0:3]
	v_mfma_f32_16x16x32_bf16 v[48:51], v[232:235], v[174:177], v[48:51]
	v_mfma_f32_16x16x32_bf16 v[40:43], v[240:243], v[174:177], v[40:43]
	v_mfma_f32_16x16x32_bf16 v[32:35], v[232:235], v[182:185], v[32:35]
	v_mfma_f32_16x16x32_bf16 v[24:27], v[240:243], v[182:185], v[24:27]
	v_mfma_f32_16x16x32_bf16 v[16:19], v[232:235], v[216:219], v[16:19]
	v_mfma_f32_16x16x32_bf16 v[8:11], v[240:243], v[216:219], v[8:11]
	v_mfma_f32_16x16x32_bf16 v[4:7], v[232:235], v[224:227], v[4:7]
	v_mfma_f32_16x16x32_bf16 v[0:3], v[240:243], v[224:227], v[0:3]
	s_add_i32 s22, 0, 0x18000
	s_barrier
	s_add_u32 s12, s18, s25
	s_addc_u32 s13, s19, 0
	s_mov_b32 m0, s27
	ds_read_b128 v[170:173], v153 offset:32768
	ds_read_b128 v[178:181], v153 offset:34816
	ds_read_b128 v[186:189], v153 offset:36864
	ds_read_b128 v[220:223], v153 offset:38912
	ds_read_b128 v[174:177], v153 offset:33792
	ds_read_b128 v[182:185], v153 offset:35840
	ds_read_b128 v[216:219], v153 offset:37888
	ds_read_b128 v[224:227], v153 offset:39936
	global_load_lds_dwordx4 v132, s[12:13]
	s_mov_b32 m0, s28
	s_nop 0
	global_load_lds_dwordx4 v128, s[12:13]
	s_waitcnt lgkmcnt(8)
	s_setprio 0
	s_waitcnt vmcnt(10)
	s_barrier
	s_waitcnt lgkmcnt(4)
	v_mfma_f32_16x16x32_bf16 v[124:127], v[154:157], v[170:173], v[124:127]
	v_mfma_f32_16x16x32_bf16 v[120:123], v[162:165], v[170:173], v[120:123]
	v_mfma_f32_16x16x32_bf16 v[116:119], v[154:157], v[178:181], v[116:119]
	v_mfma_f32_16x16x32_bf16 v[108:111], v[162:165], v[178:181], v[108:111]
	v_mfma_f32_16x16x32_bf16 v[100:103], v[154:157], v[186:189], v[100:103]
	v_mfma_f32_16x16x32_bf16 v[92:95], v[162:165], v[186:189], v[92:95]
	v_mfma_f32_16x16x32_bf16 v[84:87], v[154:157], v[220:223], v[84:87]
	v_mfma_f32_16x16x32_bf16 v[76:79], v[162:165], v[220:223], v[76:79]
	s_waitcnt lgkmcnt(0)
	v_mfma_f32_16x16x32_bf16 v[124:127], v[158:161], v[174:177], v[124:127]
	v_mfma_f32_16x16x32_bf16 v[120:123], v[166:169], v[174:177], v[120:123]
	v_mfma_f32_16x16x32_bf16 v[116:119], v[158:161], v[182:185], v[116:119]
	v_mfma_f32_16x16x32_bf16 v[108:111], v[166:169], v[182:185], v[108:111]
	v_mfma_f32_16x16x32_bf16 v[100:103], v[158:161], v[216:219], v[100:103]
	v_mfma_f32_16x16x32_bf16 v[92:95], v[166:169], v[216:219], v[92:95]
	v_mfma_f32_16x16x32_bf16 v[84:87], v[158:161], v[224:227], v[84:87]
	v_mfma_f32_16x16x32_bf16 v[76:79], v[166:169], v[224:227], v[76:79]
	s_barrier
	s_setprio 1
	s_add_i32 s12, 0, 0x1c000
	s_add_i32 s13, s22, s26
	v_add_u32_e32 v200, s12, v152
	v_lshl_add_u64 v[190:191], v[190:191], 0, s[66:67]
	s_mov_b32 m0, s13
	ds_read_b128 v[228:231], v200
	ds_read_b128 v[236:239], v200 offset:2048
	ds_read_b128 v[232:235], v200 offset:1024
	ds_read_b128 v[240:243], v200 offset:3072
	global_load_lds_dwordx4 v[190:191], off
	v_lshl_add_u64 v[190:191], v[244:245], 0, s[66:67]
	s_add_i32 m0, s13, 0x2000
	s_nop 0
	global_load_lds_dwordx4 v[190:191], off
	s_setprio 0
	s_waitcnt vmcnt(10)
	s_barrier
	s_waitcnt lgkmcnt(2)
	v_mfma_f32_16x16x32_bf16 v[112:115], v[228:231], v[170:173], v[112:115]
	v_mfma_f32_16x16x32_bf16 v[104:107], v[236:239], v[170:173], v[104:107]
	v_mfma_f32_16x16x32_bf16 v[96:99], v[228:231], v[178:181], v[96:99]
	v_mfma_f32_16x16x32_bf16 v[88:91], v[236:239], v[178:181], v[88:91]
	v_mfma_f32_16x16x32_bf16 v[80:83], v[228:231], v[186:189], v[80:83]
	v_mfma_f32_16x16x32_bf16 v[72:75], v[236:239], v[186:189], v[72:75]
	v_mfma_f32_16x16x32_bf16 v[68:71], v[228:231], v[220:223], v[68:71]
	v_mfma_f32_16x16x32_bf16 v[64:67], v[236:239], v[220:223], v[64:67]
	s_waitcnt lgkmcnt(0)
	v_mfma_f32_16x16x32_bf16 v[112:115], v[232:235], v[174:177], v[112:115]
	v_mfma_f32_16x16x32_bf16 v[104:107], v[240:243], v[174:177], v[104:107]
	v_mfma_f32_16x16x32_bf16 v[96:99], v[232:235], v[182:185], v[96:99]
	v_mfma_f32_16x16x32_bf16 v[88:91], v[240:243], v[182:185], v[88:91]
	v_mfma_f32_16x16x32_bf16 v[80:83], v[232:235], v[216:219], v[80:83]
	v_mfma_f32_16x16x32_bf16 v[72:75], v[240:243], v[216:219], v[72:75]
	v_mfma_f32_16x16x32_bf16 v[68:71], v[232:235], v[224:227], v[68:71]
	v_mfma_f32_16x16x32_bf16 v[64:67], v[240:243], v[224:227], v[64:67]
	s_mov_b32 m0, s30
	s_barrier
	ds_read_b128 v[170:173], v153 offset:49152
	ds_read_b128 v[178:181], v153 offset:51200
	ds_read_b128 v[186:189], v153 offset:53248
	ds_read_b128 v[220:223], v153 offset:55296
	ds_read_b128 v[174:177], v153 offset:50176
	ds_read_b128 v[182:185], v153 offset:52224
	ds_read_b128 v[216:219], v153 offset:54272
	ds_read_b128 v[224:227], v153 offset:56320
	s_add_u32 s98, s18, 0x80
	s_addc_u32 s99, s19, 0
	global_load_lds_dwordx4 v132, s[98:99]
	s_mov_b32 m0, s31
	s_nop 0
	global_load_lds_dwordx4 v128, s[98:99]
	s_setprio 0
	s_waitcnt vmcnt(10)
	s_barrier
	s_waitcnt lgkmcnt(4)
	v_mfma_f32_16x16x32_bf16 v[60:63], v[154:157], v[170:173], v[60:63]
	v_mfma_f32_16x16x32_bf16 v[56:59], v[162:165], v[170:173], v[56:59]
	v_mfma_f32_16x16x32_bf16 v[52:55], v[154:157], v[178:181], v[52:55]
	v_mfma_f32_16x16x32_bf16 v[44:47], v[162:165], v[178:181], v[44:47]
	v_mfma_f32_16x16x32_bf16 v[36:39], v[154:157], v[186:189], v[36:39]
	v_mfma_f32_16x16x32_bf16 v[28:31], v[162:165], v[186:189], v[28:31]
	v_mfma_f32_16x16x32_bf16 v[20:23], v[154:157], v[220:223], v[20:23]
	v_mfma_f32_16x16x32_bf16 v[12:15], v[162:165], v[220:223], v[12:15]
	s_waitcnt lgkmcnt(0)
	v_mfma_f32_16x16x32_bf16 v[60:63], v[158:161], v[174:177], v[60:63]
	v_mfma_f32_16x16x32_bf16 v[56:59], v[166:169], v[174:177], v[56:59]
	v_mfma_f32_16x16x32_bf16 v[52:55], v[158:161], v[182:185], v[52:55]
	v_mfma_f32_16x16x32_bf16 v[44:47], v[166:169], v[182:185], v[44:47]
	v_mfma_f32_16x16x32_bf16 v[36:39], v[158:161], v[216:219], v[36:39]
	v_mfma_f32_16x16x32_bf16 v[28:31], v[166:169], v[216:219], v[28:31]
	v_mfma_f32_16x16x32_bf16 v[20:23], v[158:161], v[224:227], v[20:23]
	v_mfma_f32_16x16x32_bf16 v[12:15], v[166:169], v[224:227], v[12:15]
	s_barrier
	s_setprio 1
	s_add_i32 s12, s12, s26
	v_lshl_add_u64 v[154:155], v[250:251], 0, s[66:67]
	s_mov_b32 m0, s12
	s_nop 0
	global_load_lds_dwordx4 v[154:155], off
	v_lshl_add_u64 v[154:155], v[252:253], 0, s[66:67]
	s_add_i32 m0, s12, 0x2000
	s_nop 0
	global_load_lds_dwordx4 v[154:155], off
	v_add_u32_e32 v166, 0x10000, v152
	ds_read_b128 v[154:157], v166
	ds_read_b128 v[158:161], v166 offset:1024
	ds_read_b128 v[162:165], v166 offset:2048
	ds_read_b128 v[166:169], v166 offset:3072
	s_setprio 0
	s_waitcnt vmcnt(10)
	s_barrier
	v_mfma_f32_16x16x32_bf16 v[48:51], v[228:231], v[170:173], v[48:51]
	v_mfma_f32_16x16x32_bf16 v[40:43], v[236:239], v[170:173], v[40:43]
	v_mfma_f32_16x16x32_bf16 v[32:35], v[228:231], v[178:181], v[32:35]
	v_mfma_f32_16x16x32_bf16 v[24:27], v[236:239], v[178:181], v[24:27]
	v_mfma_f32_16x16x32_bf16 v[16:19], v[228:231], v[186:189], v[16:19]
	v_mfma_f32_16x16x32_bf16 v[8:11], v[236:239], v[186:189], v[8:11]
	v_mfma_f32_16x16x32_bf16 v[4:7], v[228:231], v[220:223], v[4:7]
	v_mfma_f32_16x16x32_bf16 v[0:3], v[236:239], v[220:223], v[0:3]
	v_mfma_f32_16x16x32_bf16 v[48:51], v[232:235], v[174:177], v[48:51]
	v_mfma_f32_16x16x32_bf16 v[40:43], v[240:243], v[174:177], v[40:43]
	v_mfma_f32_16x16x32_bf16 v[32:35], v[232:235], v[182:185], v[32:35]
	v_mfma_f32_16x16x32_bf16 v[24:27], v[240:243], v[182:185], v[24:27]
	v_mfma_f32_16x16x32_bf16 v[16:19], v[232:235], v[216:219], v[16:19]
	v_mfma_f32_16x16x32_bf16 v[8:11], v[240:243], v[216:219], v[8:11]
	v_mfma_f32_16x16x32_bf16 v[4:7], v[232:235], v[224:227], v[4:7]
	v_mfma_f32_16x16x32_bf16 v[0:3], v[240:243], v[224:227], v[0:3]
	s_cmp_ge_u32 s35, s29
	s_mov_b64 s[12:13], s[16:17]
	s_mov_b32 s18, s35
	s_barrier
	s_cbranch_scc0 .LBB0_70
	s_waitcnt lgkmcnt(0)
	s_and_b64 s[6:7], s[6:7], exec
	v_mov_b32_e32 v128, v135
	s_mov_b64 s[6:7], s[0:1]
	s_load_dwordx2 s[6:7], s[6:7], 0x88
	s_cselect_b32 s3, 0x2000, 0
	v_readfirstlane_b32 s5, v128
	v_lshrrev_b32_e32 v129, 2, v128
	v_cvt_pk_bf16_f32 v104, v104, v105
	s_waitcnt lgkmcnt(0)
	s_add_u32 s6, s6, 0xfea4400
	s_addc_u32 s7, s7, 0
	s_ashr_i32 s8, s5, 2
	s_andn2_b32 s8, s8, 63
	v_and_or_b32 v128, v128, 15, s8
	s_lshr_b32 s5, s5, 1
	v_lshl_add_u32 v150, s2, 8, v128
	s_lshl_b32 s2, s4, s15
	s_and_b32 s5, s5, 0x60
	s_add_i32 s2, s2, s3
	v_and_or_b32 v132, v129, 12, s5
	v_add_u32_e32 v130, s2, v150
	v_mov_b64_e32 v[128:129], s[6:7]
	v_mad_i64_i32 v[130:131], s[4:5], v130, s96, v[128:129]
	s_lshl_b32 s58, s58, 9
	v_lshl_add_u64 v[130:131], v[130:131], 0, s[58:59]
	v_lshlrev_b32_e32 v132, 1, v132
	v_lshl_add_u64 v[130:131], v[130:131], 0, v[132:133]
	v_cvt_pk_bf16_f32 v105, v106, v107
	global_store_dwordx2 v[130:131], v[104:105], off offset:1824
	v_add3_u32 v104, s2, 16, v150
	v_mad_i64_i32 v[104:105], s[4:5], v104, s96, v[128:129]
	v_lshl_add_u64 v[104:105], v[104:105], 0, s[58:59]
	v_lshl_add_u64 v[104:105], v[104:105], 0, v[132:133]
	v_cvt_pk_bf16_f32 v88, v88, v89
	v_cvt_pk_bf16_f32 v89, v90, v91
	global_store_dwordx2 v[104:105], v[88:89], off offset:1824
	v_add3_u32 v88, s2, 32, v150
	v_mad_i64_i32 v[88:89], s[4:5], v88, s96, v[128:129]
	v_lshl_add_u64 v[88:89], v[88:89], 0, s[58:59]
	v_lshl_add_u64 v[88:89], v[88:89], 0, v[132:133]
	v_cvt_pk_bf16_f32 v72, v72, v73
	v_cvt_pk_bf16_f32 v73, v74, v75
	global_store_dwordx2 v[88:89], v[72:73], off offset:1824
	v_add3_u32 v72, s2, 48, v150
	v_mad_i64_i32 v[72:73], s[4:5], v72, s96, v[128:129]
	v_lshl_add_u64 v[72:73], v[72:73], 0, s[58:59]
	v_lshl_add_u64 v[72:73], v[72:73], 0, v[132:133]
	v_cvt_pk_bf16_f32 v64, v64, v65
	s_add_i32 s3, s2, 0x80
	v_cvt_pk_bf16_f32 v65, v66, v67
	global_store_dwordx2 v[72:73], v[64:65], off offset:1824
	v_add_u32_e32 v64, s3, v150
	v_mad_i64_i32 v[64:65], s[4:5], v64, s96, v[128:129]
	v_lshl_add_u64 v[64:65], v[64:65], 0, s[58:59]
	v_lshl_add_u64 v[64:65], v[64:65], 0, v[132:133]
	v_cvt_pk_bf16_f32 v40, v40, v41
	s_add_i32 s3, s2, 0x90
	v_cvt_pk_bf16_f32 v41, v42, v43
	global_store_dwordx2 v[64:65], v[40:41], off offset:1824
	v_add_u32_e32 v40, s3, v150
	v_mad_i64_i32 v[40:41], s[4:5], v40, s96, v[128:129]
	v_lshl_add_u64 v[40:41], v[40:41], 0, s[58:59]
	v_lshl_add_u64 v[40:41], v[40:41], 0, v[132:133]
	v_cvt_pk_bf16_f32 v24, v24, v25
	s_add_i32 s3, s2, 0xa0
	v_cvt_pk_bf16_f32 v25, v26, v27
	global_store_dwordx2 v[40:41], v[24:25], off offset:1824
	v_add_u32_e32 v24, s3, v150
	v_mad_i64_i32 v[24:25], s[4:5], v24, s96, v[128:129]
	v_lshl_add_u64 v[24:25], v[24:25], 0, s[58:59]
	v_lshl_add_u64 v[24:25], v[24:25], 0, v[132:133]
	v_cvt_pk_bf16_f32 v8, v8, v9
	s_addk_i32 s2, 0xb0
	v_cvt_pk_bf16_f32 v9, v10, v11
	global_store_dwordx2 v[24:25], v[8:9], off offset:1824
	v_add_u32_e32 v8, s2, v150
	v_mad_i64_i32 v[8:9], s[2:3], v8, s96, v[128:129]
	v_lshl_add_u64 v[8:9], v[8:9], 0, s[58:59]
	v_cvt_pk_bf16_f32 v106, v116, v117
	v_cvt_pk_bf16_f32 v107, v118, v119
	v_cvt_pk_bf16_f32 v90, v100, v101
	v_cvt_pk_bf16_f32 v91, v102, v103
	v_cvt_pk_bf16_f32 v74, v84, v85
	v_cvt_pk_bf16_f32 v75, v86, v87
	v_cvt_pk_bf16_f32 v42, v52, v53
	v_cvt_pk_bf16_f32 v43, v54, v55
	v_cvt_pk_bf16_f32 v26, v36, v37
	v_cvt_pk_bf16_f32 v27, v38, v39
	v_lshl_add_u64 v[8:9], v[8:9], 0, v[132:133]
	v_cvt_pk_bf16_f32 v10, v20, v21
	v_cvt_pk_bf16_f32 v11, v22, v23
	v_cvt_pk_bf16_f32 v124, v124, v125
	v_cvt_pk_bf16_f32 v125, v126, v127
	global_store_dwordx2 v[130:131], v[124:125], off offset:1536
	v_cvt_pk_bf16_f32 v120, v120, v121
	v_cvt_pk_bf16_f32 v121, v122, v123
	global_store_dwordx2 v[130:131], v[120:121], off offset:1568
	v_cvt_pk_bf16_f32 v112, v112, v113
	v_cvt_pk_bf16_f32 v113, v114, v115
	global_store_dwordx2 v[130:131], v[112:113], off offset:1792
	global_store_dwordx2 v[104:105], v[106:107], off offset:1536
	v_cvt_pk_bf16_f32 v106, v108, v109
	v_cvt_pk_bf16_f32 v107, v110, v111
	global_store_dwordx2 v[104:105], v[106:107], off offset:1568
	v_cvt_pk_bf16_f32 v96, v96, v97
	v_cvt_pk_bf16_f32 v97, v98, v99
	global_store_dwordx2 v[104:105], v[96:97], off offset:1792
	global_store_dwordx2 v[88:89], v[90:91], off offset:1536
	v_cvt_pk_bf16_f32 v90, v92, v93
	v_cvt_pk_bf16_f32 v91, v94, v95
	global_store_dwordx2 v[88:89], v[90:91], off offset:1568
	v_cvt_pk_bf16_f32 v80, v80, v81
	v_cvt_pk_bf16_f32 v81, v82, v83
	global_store_dwordx2 v[88:89], v[80:81], off offset:1792
	global_store_dwordx2 v[72:73], v[74:75], off offset:1536
	v_cvt_pk_bf16_f32 v74, v76, v77
	v_cvt_pk_bf16_f32 v75, v78, v79
	global_store_dwordx2 v[72:73], v[74:75], off offset:1568
	v_cvt_pk_bf16_f32 v68, v68, v69
	v_cvt_pk_bf16_f32 v69, v70, v71
	global_store_dwordx2 v[72:73], v[68:69], off offset:1792
	v_cvt_pk_bf16_f32 v60, v60, v61
	v_cvt_pk_bf16_f32 v61, v62, v63
	global_store_dwordx2 v[64:65], v[60:61], off offset:1536
	v_cvt_pk_bf16_f32 v56, v56, v57
	v_cvt_pk_bf16_f32 v57, v58, v59
	global_store_dwordx2 v[64:65], v[56:57], off offset:1568
	v_cvt_pk_bf16_f32 v48, v48, v49
	v_cvt_pk_bf16_f32 v49, v50, v51
	global_store_dwordx2 v[64:65], v[48:49], off offset:1792
	global_store_dwordx2 v[40:41], v[42:43], off offset:1536
	v_cvt_pk_bf16_f32 v42, v44, v45
	v_cvt_pk_bf16_f32 v43, v46, v47
	global_store_dwordx2 v[40:41], v[42:43], off offset:1568
	v_cvt_pk_bf16_f32 v32, v32, v33
	v_cvt_pk_bf16_f32 v33, v34, v35
	global_store_dwordx2 v[40:41], v[32:33], off offset:1792
	global_store_dwordx2 v[24:25], v[26:27], off offset:1536
	v_cvt_pk_bf16_f32 v26, v28, v29
	v_cvt_pk_bf16_f32 v27, v30, v31
	global_store_dwordx2 v[24:25], v[26:27], off offset:1568
	v_cvt_pk_bf16_f32 v16, v16, v17
	v_cvt_pk_bf16_f32 v17, v18, v19
	global_store_dwordx2 v[24:25], v[16:17], off offset:1792
	global_store_dwordx2 v[8:9], v[10:11], off offset:1536
	v_cvt_pk_bf16_f32 v10, v12, v13
	v_cvt_pk_bf16_f32 v11, v14, v15
	global_store_dwordx2 v[8:9], v[10:11], off offset:1568
	v_cvt_pk_bf16_f32 v4, v4, v5
	v_cvt_pk_bf16_f32 v5, v6, v7
	global_store_dwordx2 v[8:9], v[4:5], off offset:1792
	v_cvt_pk_bf16_f32 v0, v0, v1
	v_cvt_pk_bf16_f32 v1, v2, v3
	global_store_dwordx2 v[8:9], v[0:1], off offset:1824
	s_waitcnt vmcnt(0)
	s_cmpk_lt_u32 s14, 0x100
	s_cbranch_scc0 .LBB0_73
	s_barrier

.LBB0_145:
	s_add_u32 s6, s2, 0xfffc0080
	s_addc_u32 s7, s3, -1
	s_add_i32 s29, 0, 0x10000
	s_cmp_eq_u32 s28, 12
	s_cselect_b32 s11, s9, s7
	s_cselect_b32 s10, s12, s6
	s_cselect_b32 s7, s13, s27
	s_cselect_b32 s6, s17, s19
	s_add_i32 m0, s50, 0xc000
	ds_read_b128 v[170:173], v216
	ds_read_b128 v[178:181], v216 offset:2048
	ds_read_b128 v[186:189], v216 offset:4096
	ds_read_b128 v[222:225], v216 offset:6144
	ds_read_b128 v[174:177], v216 offset:1024
	ds_read_b128 v[182:185], v216 offset:3072
	ds_read_b128 v[218:221], v216 offset:5120
	ds_read_b128 v[226:229], v216 offset:7168
	global_load_lds_dwordx4 v154, s[2:3]
	s_add_i32 m0, s50, 0xe000
	s_nop 0
	global_load_lds_dwordx4 v156, s[2:3]
	s_waitcnt lgkmcnt(8)
	s_setprio 0
	s_waitcnt vmcnt(10)
	s_barrier
	s_waitcnt lgkmcnt(4)
	v_mfma_f32_16x16x32_bf16 v[124:127], v[128:131], v[170:173], v[124:127]
	v_mfma_f32_16x16x32_bf16 v[120:123], v[162:165], v[170:173], v[120:123]
	v_mfma_f32_16x16x32_bf16 v[108:111], v[128:131], v[178:181], v[108:111]
	v_mfma_f32_16x16x32_bf16 v[104:107], v[162:165], v[178:181], v[104:107]
	v_mfma_f32_16x16x32_bf16 v[92:95], v[128:131], v[186:189], v[92:95]
	v_mfma_f32_16x16x32_bf16 v[88:91], v[162:165], v[186:189], v[88:91]
	v_mfma_f32_16x16x32_bf16 v[76:79], v[128:131], v[222:225], v[76:79]
	v_mfma_f32_16x16x32_bf16 v[72:75], v[162:165], v[222:225], v[72:75]
	s_waitcnt lgkmcnt(0)
	v_mfma_f32_16x16x32_bf16 v[124:127], v[158:161], v[174:177], v[124:127]
	v_mfma_f32_16x16x32_bf16 v[120:123], v[166:169], v[174:177], v[120:123]
	v_mfma_f32_16x16x32_bf16 v[108:111], v[158:161], v[182:185], v[108:111]
	v_mfma_f32_16x16x32_bf16 v[104:107], v[166:169], v[182:185], v[104:107]
	v_mfma_f32_16x16x32_bf16 v[92:95], v[158:161], v[218:221], v[92:95]
	v_mfma_f32_16x16x32_bf16 v[88:91], v[166:169], v[218:221], v[88:91]
	v_mfma_f32_16x16x32_bf16 v[76:79], v[158:161], v[226:229], v[76:79]
	v_mfma_f32_16x16x32_bf16 v[72:75], v[166:169], v[226:229], v[72:75]
	s_barrier
	s_setprio 1
	s_add_i32 s34, 0, 0x14000
	s_add_i32 s29, s29, s15
	v_add_u32_e32 v132, s34, v215
	s_mov_b32 m0, s29
	ds_read_b128 v[230:233], v132
	ds_read_b128 v[238:241], v132 offset:2048
	ds_read_b128 v[234:237], v132 offset:1024
	ds_read_b128 v[242:245], v132 offset:3072
	global_load_lds_dwordx4 v150, s[6:7]
	s_add_i32 m0, s29, 0x2000
	s_nop 0
	global_load_lds_dwordx4 v152, s[6:7]
	s_setprio 0
	s_waitcnt vmcnt(10)
	s_barrier
	s_waitcnt lgkmcnt(2)
	v_mfma_f32_16x16x32_bf16 v[116:119], v[230:233], v[170:173], v[116:119]
	v_mfma_f32_16x16x32_bf16 v[112:115], v[238:241], v[170:173], v[112:115]
	v_mfma_f32_16x16x32_bf16 v[100:103], v[230:233], v[178:181], v[100:103]
	v_mfma_f32_16x16x32_bf16 v[96:99], v[238:241], v[178:181], v[96:99]
	v_mfma_f32_16x16x32_bf16 v[84:87], v[230:233], v[186:189], v[84:87]
	v_mfma_f32_16x16x32_bf16 v[80:83], v[238:241], v[186:189], v[80:83]
	v_mfma_f32_16x16x32_bf16 v[68:71], v[230:233], v[222:225], v[68:71]
	v_mfma_f32_16x16x32_bf16 v[64:67], v[238:241], v[222:225], v[64:67]
	s_waitcnt lgkmcnt(0)
	v_mfma_f32_16x16x32_bf16 v[116:119], v[234:237], v[174:177], v[116:119]
	v_mfma_f32_16x16x32_bf16 v[112:115], v[242:245], v[174:177], v[112:115]
	v_mfma_f32_16x16x32_bf16 v[100:103], v[234:237], v[182:185], v[100:103]
	v_mfma_f32_16x16x32_bf16 v[96:99], v[242:245], v[182:185], v[96:99]
	v_mfma_f32_16x16x32_bf16 v[84:87], v[234:237], v[218:221], v[84:87]
	v_mfma_f32_16x16x32_bf16 v[80:83], v[242:245], v[218:221], v[80:83]
	v_mfma_f32_16x16x32_bf16 v[68:71], v[234:237], v[226:229], v[68:71]
	v_mfma_f32_16x16x32_bf16 v[64:67], v[242:245], v[226:229], v[64:67]
	s_mov_b32 m0, s50
	v_lshl_add_u64 v[248:249], s[10:11], 0, v[150:151]
	s_barrier
	ds_read_b128 v[170:173], v216 offset:16384
	ds_read_b128 v[178:181], v216 offset:18432
	ds_read_b128 v[186:189], v216 offset:20480
	ds_read_b128 v[222:225], v216 offset:22528
	ds_read_b128 v[174:177], v216 offset:17408
	ds_read_b128 v[182:185], v216 offset:19456
	ds_read_b128 v[218:221], v216 offset:21504
	ds_read_b128 v[226:229], v216 offset:23552
	global_load_lds_dwordx4 v150, s[10:11]
	v_lshl_add_u64 v[250:251], s[10:11], 0, v[152:153]
	s_mov_b32 m0, s51
	s_nop 0
	global_load_lds_dwordx4 v152, s[10:11]
	s_setprio 0
	s_waitcnt vmcnt(10)
	s_barrier
	s_waitcnt lgkmcnt(4)
	v_mfma_f32_16x16x32_bf16 v[60:63], v[128:131], v[170:173], v[60:63]
	v_mfma_f32_16x16x32_bf16 v[56:59], v[162:165], v[170:173], v[56:59]
	v_mfma_f32_16x16x32_bf16 v[44:47], v[128:131], v[178:181], v[44:47]
	v_mfma_f32_16x16x32_bf16 v[40:43], v[162:165], v[178:181], v[40:43]
	v_mfma_f32_16x16x32_bf16 v[28:31], v[128:131], v[186:189], v[28:31]
	v_mfma_f32_16x16x32_bf16 v[24:27], v[162:165], v[186:189], v[24:27]
	v_mfma_f32_16x16x32_bf16 v[12:15], v[128:131], v[222:225], v[12:15]
	v_mfma_f32_16x16x32_bf16 v[8:11], v[162:165], v[222:225], v[8:11]
	s_waitcnt lgkmcnt(0)
	v_mfma_f32_16x16x32_bf16 v[60:63], v[158:161], v[174:177], v[60:63]
	v_mfma_f32_16x16x32_bf16 v[56:59], v[166:169], v[174:177], v[56:59]
	v_mfma_f32_16x16x32_bf16 v[44:47], v[158:161], v[182:185], v[44:47]
	v_mfma_f32_16x16x32_bf16 v[40:43], v[166:169], v[182:185], v[40:43]
	v_mfma_f32_16x16x32_bf16 v[28:31], v[158:161], v[218:221], v[28:31]
	v_mfma_f32_16x16x32_bf16 v[24:27], v[166:169], v[218:221], v[24:27]
	v_mfma_f32_16x16x32_bf16 v[12:15], v[158:161], v[226:229], v[12:15]
	v_mfma_f32_16x16x32_bf16 v[8:11], v[166:169], v[226:229], v[8:11]
	s_barrier
	s_setprio 1
	s_add_u32 s30, s6, 0x40000
	s_addc_u32 s31, s7, 0
	s_add_i32 s29, s34, s15
	s_mov_b32 m0, s29
	s_nop 0
	global_load_lds_dwordx4 v150, s[30:31]
	s_add_i32 m0, s29, 0x2000
	s_nop 0
	global_load_lds_dwordx4 v152, s[30:31]
	v_add_u32_e32 v166, 0x18000, v215
	ds_read_b128 v[128:131], v166
	ds_read_b128 v[158:161], v166 offset:1024
	ds_read_b128 v[162:165], v166 offset:2048
	ds_read_b128 v[166:169], v166 offset:3072
	s_setprio 0
	s_waitcnt vmcnt(10)
	s_barrier
	v_mfma_f32_16x16x32_bf16 v[52:55], v[230:233], v[170:173], v[52:55]
	v_mfma_f32_16x16x32_bf16 v[48:51], v[238:241], v[170:173], v[48:51]
	v_mfma_f32_16x16x32_bf16 v[36:39], v[230:233], v[178:181], v[36:39]
	v_mfma_f32_16x16x32_bf16 v[32:35], v[238:241], v[178:181], v[32:35]
	v_mfma_f32_16x16x32_bf16 v[20:23], v[230:233], v[186:189], v[20:23]
	v_mfma_f32_16x16x32_bf16 v[16:19], v[238:241], v[186:189], v[16:19]
	v_mfma_f32_16x16x32_bf16 v[4:7], v[230:233], v[222:225], v[4:7]
	v_mfma_f32_16x16x32_bf16 v[0:3], v[238:241], v[222:225], v[0:3]
	v_mfma_f32_16x16x32_bf16 v[52:55], v[234:237], v[174:177], v[52:55]
	v_mfma_f32_16x16x32_bf16 v[48:51], v[242:245], v[174:177], v[48:51]
	v_mfma_f32_16x16x32_bf16 v[36:39], v[234:237], v[182:185], v[36:39]
	v_mfma_f32_16x16x32_bf16 v[32:35], v[242:245], v[182:185], v[32:35]
	v_mfma_f32_16x16x32_bf16 v[20:23], v[234:237], v[218:221], v[20:23]
	v_mfma_f32_16x16x32_bf16 v[16:19], v[242:245], v[218:221], v[16:19]
	v_mfma_f32_16x16x32_bf16 v[4:7], v[234:237], v[226:229], v[4:7]
	v_mfma_f32_16x16x32_bf16 v[0:3], v[242:245], v[226:229], v[0:3]
	s_add_i32 s29, 0, 0x18000
	s_barrier
	s_add_u32 s10, s10, 0x40000
	s_addc_u32 s11, s11, 0
	s_mov_b32 m0, s36
	ds_read_b128 v[170:173], v216 offset:32768
	ds_read_b128 v[178:181], v216 offset:34816
	ds_read_b128 v[186:189], v216 offset:36864
	ds_read_b128 v[222:225], v216 offset:38912
	ds_read_b128 v[174:177], v216 offset:33792
	ds_read_b128 v[182:185], v216 offset:35840
	ds_read_b128 v[218:221], v216 offset:37888
	ds_read_b128 v[226:229], v216 offset:39936
	global_load_lds_dwordx4 v150, s[10:11]
	s_mov_b32 m0, s37
	s_nop 0
	global_load_lds_dwordx4 v152, s[10:11]
	s_waitcnt lgkmcnt(8)
	s_setprio 0
	s_waitcnt vmcnt(10)
	s_barrier
	s_waitcnt lgkmcnt(4)
	v_mfma_f32_16x16x32_bf16 v[124:127], v[128:131], v[170:173], v[124:127]
	v_mfma_f32_16x16x32_bf16 v[120:123], v[162:165], v[170:173], v[120:123]
	v_mfma_f32_16x16x32_bf16 v[108:111], v[128:131], v[178:181], v[108:111]
	v_mfma_f32_16x16x32_bf16 v[104:107], v[162:165], v[178:181], v[104:107]
	v_mfma_f32_16x16x32_bf16 v[92:95], v[128:131], v[186:189], v[92:95]
	v_mfma_f32_16x16x32_bf16 v[88:91], v[162:165], v[186:189], v[88:91]
	v_mfma_f32_16x16x32_bf16 v[76:79], v[128:131], v[222:225], v[76:79]
	v_mfma_f32_16x16x32_bf16 v[72:75], v[162:165], v[222:225], v[72:75]
	s_waitcnt lgkmcnt(0)
	v_mfma_f32_16x16x32_bf16 v[124:127], v[158:161], v[174:177], v[124:127]
	v_mfma_f32_16x16x32_bf16 v[120:123], v[166:169], v[174:177], v[120:123]
	v_mfma_f32_16x16x32_bf16 v[108:111], v[158:161], v[182:185], v[108:111]
	v_mfma_f32_16x16x32_bf16 v[104:107], v[166:169], v[182:185], v[104:107]
	v_mfma_f32_16x16x32_bf16 v[92:95], v[158:161], v[218:221], v[92:95]
	v_mfma_f32_16x16x32_bf16 v[88:91], v[166:169], v[218:221], v[88:91]
	v_mfma_f32_16x16x32_bf16 v[76:79], v[158:161], v[226:229], v[76:79]
	v_mfma_f32_16x16x32_bf16 v[72:75], v[166:169], v[226:229], v[72:75]
	s_barrier
	s_setprio 1
	s_add_i32 s10, 0, 0x1c000
	s_add_i32 s11, s29, s15
	v_add_u32_e32 v132, s10, v215
	s_mov_b32 m0, s11
	ds_read_b128 v[230:233], v132
	ds_read_b128 v[238:241], v132 offset:2048
	ds_read_b128 v[234:237], v132 offset:1024
	ds_read_b128 v[242:245], v132 offset:3072
	s_add_u32 s98, s6, 0x80
	s_addc_u32 s99, s7, 0
	global_load_lds_dwordx4 v150, s[98:99]
	s_add_i32 m0, s11, 0x2000
	s_nop 0
	global_load_lds_dwordx4 v152, s[98:99]
	s_setprio 0
	s_waitcnt vmcnt(10)
	s_barrier
	s_waitcnt lgkmcnt(2)
	v_mfma_f32_16x16x32_bf16 v[116:119], v[230:233], v[170:173], v[116:119]
	v_mfma_f32_16x16x32_bf16 v[112:115], v[238:241], v[170:173], v[112:115]
	v_mfma_f32_16x16x32_bf16 v[100:103], v[230:233], v[178:181], v[100:103]
	v_mfma_f32_16x16x32_bf16 v[96:99], v[238:241], v[178:181], v[96:99]
	v_mfma_f32_16x16x32_bf16 v[84:87], v[230:233], v[186:189], v[84:87]
	v_mfma_f32_16x16x32_bf16 v[80:83], v[238:241], v[186:189], v[80:83]
	v_mfma_f32_16x16x32_bf16 v[68:71], v[230:233], v[222:225], v[68:71]
	v_mfma_f32_16x16x32_bf16 v[64:67], v[238:241], v[222:225], v[64:67]
	s_waitcnt lgkmcnt(0)
	v_mfma_f32_16x16x32_bf16 v[116:119], v[234:237], v[174:177], v[116:119]
	v_mfma_f32_16x16x32_bf16 v[112:115], v[242:245], v[174:177], v[112:115]
	v_mfma_f32_16x16x32_bf16 v[100:103], v[234:237], v[182:185], v[100:103]
	v_mfma_f32_16x16x32_bf16 v[96:99], v[242:245], v[182:185], v[96:99]
	v_mfma_f32_16x16x32_bf16 v[84:87], v[234:237], v[218:221], v[84:87]
	v_mfma_f32_16x16x32_bf16 v[80:83], v[242:245], v[218:221], v[80:83]
	v_mfma_f32_16x16x32_bf16 v[68:71], v[234:237], v[226:229], v[68:71]
	v_mfma_f32_16x16x32_bf16 v[64:67], v[242:245], v[226:229], v[64:67]
	s_mov_b32 m0, s52
	v_lshl_add_u64 v[190:191], v[248:249], 0, s[66:67]
	s_barrier
	ds_read_b128 v[170:173], v216 offset:49152
	ds_read_b128 v[178:181], v216 offset:51200
	ds_read_b128 v[186:189], v216 offset:53248
	ds_read_b128 v[222:225], v216 offset:55296
	ds_read_b128 v[174:177], v216 offset:50176
	ds_read_b128 v[182:185], v216 offset:52224
	ds_read_b128 v[218:221], v216 offset:54272
	ds_read_b128 v[226:229], v216 offset:56320
	global_load_lds_dwordx4 v[190:191], off
	v_lshl_add_u64 v[190:191], v[250:251], 0, s[66:67]
	s_mov_b32 m0, s53
	s_nop 0
	global_load_lds_dwordx4 v[190:191], off
	s_setprio 0
	s_waitcnt vmcnt(10)
	s_barrier
	s_waitcnt lgkmcnt(4)
	v_mfma_f32_16x16x32_bf16 v[60:63], v[128:131], v[170:173], v[60:63]
	v_mfma_f32_16x16x32_bf16 v[56:59], v[162:165], v[170:173], v[56:59]
	v_mfma_f32_16x16x32_bf16 v[44:47], v[128:131], v[178:181], v[44:47]
	v_mfma_f32_16x16x32_bf16 v[40:43], v[162:165], v[178:181], v[40:43]
	v_mfma_f32_16x16x32_bf16 v[28:31], v[128:131], v[186:189], v[28:31]
	v_mfma_f32_16x16x32_bf16 v[24:27], v[162:165], v[186:189], v[24:27]
	v_mfma_f32_16x16x32_bf16 v[12:15], v[128:131], v[222:225], v[12:15]
	v_mfma_f32_16x16x32_bf16 v[8:11], v[162:165], v[222:225], v[8:11]
	s_waitcnt lgkmcnt(0)
	v_mfma_f32_16x16x32_bf16 v[60:63], v[158:161], v[174:177], v[60:63]
	v_mfma_f32_16x16x32_bf16 v[56:59], v[166:169], v[174:177], v[56:59]
	v_mfma_f32_16x16x32_bf16 v[44:47], v[158:161], v[182:185], v[44:47]
	v_mfma_f32_16x16x32_bf16 v[40:43], v[166:169], v[182:185], v[40:43]
	v_mfma_f32_16x16x32_bf16 v[28:31], v[158:161], v[218:221], v[28:31]
	v_mfma_f32_16x16x32_bf16 v[24:27], v[166:169], v[218:221], v[24:27]
	v_mfma_f32_16x16x32_bf16 v[12:15], v[158:161], v[226:229], v[12:15]
	v_mfma_f32_16x16x32_bf16 v[8:11], v[166:169], v[226:229], v[8:11]
	s_barrier
	s_setprio 1
	s_add_u32 s6, s6, 0x40080
	s_addc_u32 s7, s7, 0
	s_add_i32 s10, s10, s15
	s_mov_b32 m0, s10
	s_nop 0
	global_load_lds_dwordx4 v150, s[6:7]
	s_add_i32 m0, s10, 0x2000
	s_nop 0
	global_load_lds_dwordx4 v152, s[6:7]
	v_add_u32_e32 v166, 0x10000, v215
	ds_read_b128 v[128:131], v166
	ds_read_b128 v[158:161], v166 offset:1024
	ds_read_b128 v[162:165], v166 offset:2048
	ds_read_b128 v[166:169], v166 offset:3072
	s_setprio 0
	s_waitcnt vmcnt(10)
	s_barrier
	v_mfma_f32_16x16x32_bf16 v[52:55], v[230:233], v[170:173], v[52:55]
	v_mfma_f32_16x16x32_bf16 v[48:51], v[238:241], v[170:173], v[48:51]
	v_mfma_f32_16x16x32_bf16 v[36:39], v[230:233], v[178:181], v[36:39]
	v_mfma_f32_16x16x32_bf16 v[32:35], v[238:241], v[178:181], v[32:35]
	v_mfma_f32_16x16x32_bf16 v[20:23], v[230:233], v[186:189], v[20:23]
	v_mfma_f32_16x16x32_bf16 v[16:19], v[238:241], v[186:189], v[16:19]
	v_mfma_f32_16x16x32_bf16 v[4:7], v[230:233], v[222:225], v[4:7]
	v_mfma_f32_16x16x32_bf16 v[0:3], v[238:241], v[222:225], v[0:3]
	v_mfma_f32_16x16x32_bf16 v[52:55], v[234:237], v[174:177], v[52:55]
	v_mfma_f32_16x16x32_bf16 v[48:51], v[242:245], v[174:177], v[48:51]
	v_mfma_f32_16x16x32_bf16 v[36:39], v[234:237], v[182:185], v[36:39]
	v_mfma_f32_16x16x32_bf16 v[32:35], v[242:245], v[182:185], v[32:35]
	v_mfma_f32_16x16x32_bf16 v[20:23], v[234:237], v[218:221], v[20:23]
	v_mfma_f32_16x16x32_bf16 v[16:19], v[242:245], v[218:221], v[16:19]
	v_mfma_f32_16x16x32_bf16 v[4:7], v[234:237], v[226:229], v[4:7]
	v_mfma_f32_16x16x32_bf16 v[0:3], v[242:245], v[226:229], v[0:3]
	s_add_i32 s28, s28, 2
	s_add_u32 s2, s2, 0x100
	s_addc_u32 s3, s3, 0
	s_add_u32 s19, s19, 0x100
	s_addc_u32 s27, s27, 0
	s_cmp_gt_u32 s28, 13
	s_barrier
	s_cbranch_scc0 .LBB0_145
	s_waitcnt lgkmcnt(0)
	v_mov_b32_e32 v166, v135
	s_mov_b64 s[2:3], s[0:1]
	v_readfirstlane_b32 s27, v166
	s_bfe_u32 s19, s27, 0x20006
	s_load_dwordx2 s[30:31], s[2:3], 0x88
	s_mov_b64 s[2:3], s[0:1]
	s_cmp_gt_i32 s8, 31
	s_load_dwordx2 s[28:29], s[2:3], 0x80
	s_cselect_b64 s[6:7], -1, 0
	s_cmp_lt_i32 s8, 32
	s_cselect_b64 s[2:3], -1, 0
	s_ashr_i32 s9, s27, 2
	s_lshl_b32 s8, s8, 8
	s_and_b32 s17, s9, 0xffffffc0
	v_and_b32_e32 v217, 15, v166
	s_add_i32 s17, s17, s8
	v_bfe_u32 v186, v166, 4, 2
	v_or_b32_e32 v158, s17, v217
	s_cmp_gt_i32 s26, 3
	s_mov_b64 s[8:9], -1
	s_cbranch_scc0 .LBB0_829
	s_cmp_gt_u32 s26, 5
	s_cbranch_scc0 .LBB0_409
	s_cmp_gt_u32 s26, 8
	s_cbranch_scc0 .LBB0_406
	s_waitcnt lgkmcnt(0)
	v_and_b32_e32 v128, 1, v166
	v_cmp_eq_u32_e64 s[8:9], 0, v128
	v_cmp_eq_u32_e32 vcc, 1, v128
	s_mov_b32 s10, 0x05040100
	s_mov_b32 s11, 0x07060302
	s_cmp_eq_u32 s6, 0
	s_cbranch_scc1 .Lvf_f_c

.LBB0_1104:
	s_add_u32 s22, s18, 0xfffc0080
	s_addc_u32 s23, s19, -1
	s_add_i32 s47, 0, 0x10000
	s_cmp_eq_u32 s46, 12
	s_cselect_b32 s25, s9, s23
	s_cselect_b32 s24, s42, s22
	s_cselect_b32 s23, s7, s45
	s_cselect_b32 s22, s43, s44
	s_add_i32 m0, s17, 0xc000
	ds_read_b128 v[172:175], v155
	ds_read_b128 v[180:183], v155 offset:2048
	ds_read_b128 v[188:191], v155 offset:4096
	ds_read_b128 v[220:223], v155 offset:6144
	ds_read_b128 v[176:179], v155 offset:1024
	ds_read_b128 v[184:187], v155 offset:3072
	ds_read_b128 v[216:219], v155 offset:5120
	ds_read_b128 v[224:227], v155 offset:7168
	global_load_lds_dwordx4 v130, s[18:19]
	s_add_i32 m0, s17, 0xe000
	s_nop 0
	global_load_lds_dwordx4 v150, s[18:19]
	s_waitcnt lgkmcnt(8)
	s_setprio 0
	s_waitcnt vmcnt(10)
	s_barrier
	s_waitcnt lgkmcnt(4)
	v_mfma_f32_16x16x32_bf16 v[124:127], v[156:159], v[172:175], v[124:127]
	v_mfma_f32_16x16x32_bf16 v[120:123], v[164:167], v[172:175], v[120:123]
	v_mfma_f32_16x16x32_bf16 v[108:111], v[156:159], v[180:183], v[108:111]
	v_mfma_f32_16x16x32_bf16 v[104:107], v[164:167], v[180:183], v[104:107]
	v_mfma_f32_16x16x32_bf16 v[92:95], v[156:159], v[188:191], v[92:95]
	v_mfma_f32_16x16x32_bf16 v[88:91], v[164:167], v[188:191], v[88:91]
	v_mfma_f32_16x16x32_bf16 v[76:79], v[156:159], v[220:223], v[76:79]
	v_mfma_f32_16x16x32_bf16 v[72:75], v[164:167], v[220:223], v[72:75]
	s_waitcnt lgkmcnt(0)
	v_mfma_f32_16x16x32_bf16 v[124:127], v[160:163], v[176:179], v[124:127]
	v_mfma_f32_16x16x32_bf16 v[120:123], v[168:171], v[176:179], v[120:123]
	v_mfma_f32_16x16x32_bf16 v[108:111], v[160:163], v[184:187], v[108:111]
	v_mfma_f32_16x16x32_bf16 v[104:107], v[168:171], v[184:187], v[104:107]
	v_mfma_f32_16x16x32_bf16 v[92:95], v[160:163], v[216:219], v[92:95]
	v_mfma_f32_16x16x32_bf16 v[88:91], v[168:171], v[216:219], v[88:91]
	v_mfma_f32_16x16x32_bf16 v[76:79], v[160:163], v[224:227], v[76:79]
	v_mfma_f32_16x16x32_bf16 v[72:75], v[168:171], v[224:227], v[72:75]
	s_barrier
	s_setprio 1
	s_add_i32 s50, 0, 0x14000
	v_add_u32_e32 v152, s50, v154
	s_add_i32 s47, s47, s29
	ds_read_b128 v[228:231], v152
	ds_read_b128 v[236:239], v152 offset:2048
	ds_read_b128 v[232:235], v152 offset:1024
	ds_read_b128 v[240:243], v152 offset:3072
	s_mov_b32 m0, s47
	s_nop 0
	global_load_lds_dwordx4 v132, s[22:23]
	s_add_i32 m0, s47, 0x2000
	s_nop 0
	global_load_lds_dwordx4 v128, s[22:23]
	s_setprio 0
	s_waitcnt vmcnt(10)
	s_barrier
	s_waitcnt lgkmcnt(2)
	v_mfma_f32_16x16x32_bf16 v[116:119], v[228:231], v[172:175], v[116:119]
	v_mfma_f32_16x16x32_bf16 v[112:115], v[236:239], v[172:175], v[112:115]
	v_mfma_f32_16x16x32_bf16 v[100:103], v[228:231], v[180:183], v[100:103]
	v_mfma_f32_16x16x32_bf16 v[96:99], v[236:239], v[180:183], v[96:99]
	v_mfma_f32_16x16x32_bf16 v[84:87], v[228:231], v[188:191], v[84:87]
	v_mfma_f32_16x16x32_bf16 v[80:83], v[236:239], v[188:191], v[80:83]
	v_mfma_f32_16x16x32_bf16 v[68:71], v[228:231], v[220:223], v[68:71]
	v_mfma_f32_16x16x32_bf16 v[64:67], v[236:239], v[220:223], v[64:67]
	s_waitcnt lgkmcnt(0)
	v_mfma_f32_16x16x32_bf16 v[116:119], v[232:235], v[176:179], v[116:119]
	v_mfma_f32_16x16x32_bf16 v[112:115], v[240:243], v[176:179], v[112:115]
	v_mfma_f32_16x16x32_bf16 v[100:103], v[232:235], v[184:187], v[100:103]
	v_mfma_f32_16x16x32_bf16 v[96:99], v[240:243], v[184:187], v[96:99]
	v_mfma_f32_16x16x32_bf16 v[84:87], v[232:235], v[216:219], v[84:87]
	v_mfma_f32_16x16x32_bf16 v[80:83], v[240:243], v[216:219], v[80:83]
	v_mfma_f32_16x16x32_bf16 v[68:71], v[232:235], v[224:227], v[68:71]
	v_mfma_f32_16x16x32_bf16 v[64:67], v[240:243], v[224:227], v[64:67]
	s_mov_b32 m0, s17
	v_lshl_add_u64 v[246:247], s[24:25], 0, v[132:133]
	s_barrier
	ds_read_b128 v[172:175], v155 offset:16384
	ds_read_b128 v[180:183], v155 offset:18432
	ds_read_b128 v[188:191], v155 offset:20480
	ds_read_b128 v[220:223], v155 offset:22528
	ds_read_b128 v[176:179], v155 offset:17408
	ds_read_b128 v[184:187], v155 offset:19456
	ds_read_b128 v[216:219], v155 offset:21504
	ds_read_b128 v[224:227], v155 offset:23552
	global_load_lds_dwordx4 v132, s[24:25]
	v_lshl_add_u64 v[248:249], s[24:25], 0, v[128:129]
	s_mov_b32 m0, s31
	s_nop 0
	global_load_lds_dwordx4 v128, s[24:25]
	s_setprio 0
	s_waitcnt vmcnt(10)
	s_barrier
	s_waitcnt lgkmcnt(4)
	v_mfma_f32_16x16x32_bf16 v[60:63], v[156:159], v[172:175], v[60:63]
	v_mfma_f32_16x16x32_bf16 v[56:59], v[164:167], v[172:175], v[56:59]
	v_mfma_f32_16x16x32_bf16 v[44:47], v[156:159], v[180:183], v[44:47]
	v_mfma_f32_16x16x32_bf16 v[40:43], v[164:167], v[180:183], v[40:43]
	v_mfma_f32_16x16x32_bf16 v[28:31], v[156:159], v[188:191], v[28:31]
	v_mfma_f32_16x16x32_bf16 v[24:27], v[164:167], v[188:191], v[24:27]
	v_mfma_f32_16x16x32_bf16 v[12:15], v[156:159], v[220:223], v[12:15]
	v_mfma_f32_16x16x32_bf16 v[8:11], v[164:167], v[220:223], v[8:11]
	s_waitcnt lgkmcnt(0)
	v_mfma_f32_16x16x32_bf16 v[60:63], v[160:163], v[176:179], v[60:63]
	v_mfma_f32_16x16x32_bf16 v[56:59], v[168:171], v[176:179], v[56:59]
	v_mfma_f32_16x16x32_bf16 v[44:47], v[160:163], v[184:187], v[44:47]
	v_mfma_f32_16x16x32_bf16 v[40:43], v[168:171], v[184:187], v[40:43]
	v_mfma_f32_16x16x32_bf16 v[28:31], v[160:163], v[216:219], v[28:31]
	v_mfma_f32_16x16x32_bf16 v[24:27], v[168:171], v[216:219], v[24:27]
	v_mfma_f32_16x16x32_bf16 v[12:15], v[160:163], v[224:227], v[12:15]
	v_mfma_f32_16x16x32_bf16 v[8:11], v[168:171], v[224:227], v[8:11]
	s_barrier
	s_setprio 1
	s_add_u32 s48, s22, 0x40000
	s_addc_u32 s49, s23, 0
	s_add_i32 s47, s50, s29
	s_mov_b32 m0, s47
	s_nop 0
	global_load_lds_dwordx4 v132, s[48:49]
	s_add_i32 m0, s47, 0x2000
	s_nop 0
	global_load_lds_dwordx4 v128, s[48:49]
	v_add_u32_e32 v168, 0x18000, v154
	ds_read_b128 v[156:159], v168
	ds_read_b128 v[160:163], v168 offset:1024
	ds_read_b128 v[164:167], v168 offset:2048
	ds_read_b128 v[168:171], v168 offset:3072
	s_setprio 0
	s_waitcnt vmcnt(10)
	s_barrier
	v_mfma_f32_16x16x32_bf16 v[52:55], v[228:231], v[172:175], v[52:55]
	v_mfma_f32_16x16x32_bf16 v[48:51], v[236:239], v[172:175], v[48:51]
	v_mfma_f32_16x16x32_bf16 v[36:39], v[228:231], v[180:183], v[36:39]
	v_mfma_f32_16x16x32_bf16 v[32:35], v[236:239], v[180:183], v[32:35]
	v_mfma_f32_16x16x32_bf16 v[20:23], v[228:231], v[188:191], v[20:23]
	v_mfma_f32_16x16x32_bf16 v[16:19], v[236:239], v[188:191], v[16:19]
	v_mfma_f32_16x16x32_bf16 v[4:7], v[228:231], v[220:223], v[4:7]
	v_mfma_f32_16x16x32_bf16 v[0:3], v[236:239], v[220:223], v[0:3]
	v_mfma_f32_16x16x32_bf16 v[52:55], v[232:235], v[176:179], v[52:55]
	v_mfma_f32_16x16x32_bf16 v[48:51], v[240:243], v[176:179], v[48:51]
	v_mfma_f32_16x16x32_bf16 v[36:39], v[232:235], v[184:187], v[36:39]
	v_mfma_f32_16x16x32_bf16 v[32:35], v[240:243], v[184:187], v[32:35]
	v_mfma_f32_16x16x32_bf16 v[20:23], v[232:235], v[216:219], v[20:23]
	v_mfma_f32_16x16x32_bf16 v[16:19], v[240:243], v[216:219], v[16:19]
	v_mfma_f32_16x16x32_bf16 v[4:7], v[232:235], v[224:227], v[4:7]
	v_mfma_f32_16x16x32_bf16 v[0:3], v[240:243], v[224:227], v[0:3]
	s_add_i32 s47, 0, 0x18000
	s_barrier
	s_add_u32 s24, s24, 0x40000
	s_addc_u32 s25, s25, 0
	s_mov_b32 m0, s34
	ds_read_b128 v[172:175], v155 offset:32768
	ds_read_b128 v[180:183], v155 offset:34816
	ds_read_b128 v[188:191], v155 offset:36864
	ds_read_b128 v[220:223], v155 offset:38912
	ds_read_b128 v[176:179], v155 offset:33792
	ds_read_b128 v[184:187], v155 offset:35840
	ds_read_b128 v[216:219], v155 offset:37888
	ds_read_b128 v[224:227], v155 offset:39936
	global_load_lds_dwordx4 v132, s[24:25]
	s_mov_b32 m0, s35
	s_nop 0
	global_load_lds_dwordx4 v128, s[24:25]
	s_waitcnt lgkmcnt(8)
	s_setprio 0
	s_waitcnt vmcnt(10)
	s_barrier
	s_waitcnt lgkmcnt(4)
	v_mfma_f32_16x16x32_bf16 v[124:127], v[156:159], v[172:175], v[124:127]
	v_mfma_f32_16x16x32_bf16 v[120:123], v[164:167], v[172:175], v[120:123]
	v_mfma_f32_16x16x32_bf16 v[108:111], v[156:159], v[180:183], v[108:111]
	v_mfma_f32_16x16x32_bf16 v[104:107], v[164:167], v[180:183], v[104:107]
	v_mfma_f32_16x16x32_bf16 v[92:95], v[156:159], v[188:191], v[92:95]
	v_mfma_f32_16x16x32_bf16 v[88:91], v[164:167], v[188:191], v[88:91]
	v_mfma_f32_16x16x32_bf16 v[76:79], v[156:159], v[220:223], v[76:79]
	v_mfma_f32_16x16x32_bf16 v[72:75], v[164:167], v[220:223], v[72:75]
	s_waitcnt lgkmcnt(0)
	v_mfma_f32_16x16x32_bf16 v[124:127], v[160:163], v[176:179], v[124:127]
	v_mfma_f32_16x16x32_bf16 v[120:123], v[168:171], v[176:179], v[120:123]
	v_mfma_f32_16x16x32_bf16 v[108:111], v[160:163], v[184:187], v[108:111]
	v_mfma_f32_16x16x32_bf16 v[104:107], v[168:171], v[184:187], v[104:107]
	v_mfma_f32_16x16x32_bf16 v[92:95], v[160:163], v[216:219], v[92:95]
	v_mfma_f32_16x16x32_bf16 v[88:91], v[168:171], v[216:219], v[88:91]
	v_mfma_f32_16x16x32_bf16 v[76:79], v[160:163], v[224:227], v[76:79]
	v_mfma_f32_16x16x32_bf16 v[72:75], v[168:171], v[224:227], v[72:75]
	s_barrier
	s_setprio 1
	s_add_i32 s24, 0, 0x1c000
	s_add_i32 s25, s47, s29
	v_add_u32_e32 v200, s24, v154
	s_mov_b32 m0, s25
	ds_read_b128 v[228:231], v200
	ds_read_b128 v[236:239], v200 offset:2048
	ds_read_b128 v[232:235], v200 offset:1024
	ds_read_b128 v[240:243], v200 offset:3072
	s_add_u32 s98, s22, 0x80
	s_addc_u32 s99, s23, 0
	global_load_lds_dwordx4 v132, s[98:99]
	s_add_i32 m0, s25, 0x2000
	s_nop 0
	global_load_lds_dwordx4 v128, s[98:99]
	s_setprio 0
	s_waitcnt vmcnt(10)
	s_barrier
	s_waitcnt lgkmcnt(2)
	v_mfma_f32_16x16x32_bf16 v[116:119], v[228:231], v[172:175], v[116:119]
	v_mfma_f32_16x16x32_bf16 v[112:115], v[236:239], v[172:175], v[112:115]
	v_mfma_f32_16x16x32_bf16 v[100:103], v[228:231], v[180:183], v[100:103]
	v_mfma_f32_16x16x32_bf16 v[96:99], v[236:239], v[180:183], v[96:99]
	v_mfma_f32_16x16x32_bf16 v[84:87], v[228:231], v[188:191], v[84:87]
	v_mfma_f32_16x16x32_bf16 v[80:83], v[236:239], v[188:191], v[80:83]
	v_mfma_f32_16x16x32_bf16 v[68:71], v[228:231], v[220:223], v[68:71]
	v_mfma_f32_16x16x32_bf16 v[64:67], v[236:239], v[220:223], v[64:67]
	s_waitcnt lgkmcnt(0)
	v_mfma_f32_16x16x32_bf16 v[116:119], v[232:235], v[176:179], v[116:119]
	v_mfma_f32_16x16x32_bf16 v[112:115], v[240:243], v[176:179], v[112:115]
	v_mfma_f32_16x16x32_bf16 v[100:103], v[232:235], v[184:187], v[100:103]
	v_mfma_f32_16x16x32_bf16 v[96:99], v[240:243], v[184:187], v[96:99]
	v_mfma_f32_16x16x32_bf16 v[84:87], v[232:235], v[216:219], v[84:87]
	v_mfma_f32_16x16x32_bf16 v[80:83], v[240:243], v[216:219], v[80:83]
	v_mfma_f32_16x16x32_bf16 v[68:71], v[232:235], v[224:227], v[68:71]
	v_mfma_f32_16x16x32_bf16 v[64:67], v[240:243], v[224:227], v[64:67]
	s_mov_b32 m0, s36
	v_lshl_add_u64 v[152:153], v[246:247], 0, s[66:67]
	s_barrier
	ds_read_b128 v[172:175], v155 offset:49152
	ds_read_b128 v[180:183], v155 offset:51200
	ds_read_b128 v[188:191], v155 offset:53248
	ds_read_b128 v[220:223], v155 offset:55296
	ds_read_b128 v[176:179], v155 offset:50176
	ds_read_b128 v[184:187], v155 offset:52224
	ds_read_b128 v[216:219], v155 offset:54272
	ds_read_b128 v[224:227], v155 offset:56320
	global_load_lds_dwordx4 v[152:153], off
	v_lshl_add_u64 v[152:153], v[248:249], 0, s[66:67]
	s_mov_b32 m0, s37
	s_nop 0
	global_load_lds_dwordx4 v[152:153], off
	s_setprio 0
	s_waitcnt vmcnt(10)
	s_barrier
	s_waitcnt lgkmcnt(4)
	v_mfma_f32_16x16x32_bf16 v[60:63], v[156:159], v[172:175], v[60:63]
	v_mfma_f32_16x16x32_bf16 v[56:59], v[164:167], v[172:175], v[56:59]
	v_mfma_f32_16x16x32_bf16 v[44:47], v[156:159], v[180:183], v[44:47]
	v_mfma_f32_16x16x32_bf16 v[40:43], v[164:167], v[180:183], v[40:43]
	v_mfma_f32_16x16x32_bf16 v[28:31], v[156:159], v[188:191], v[28:31]
	v_mfma_f32_16x16x32_bf16 v[24:27], v[164:167], v[188:191], v[24:27]
	v_mfma_f32_16x16x32_bf16 v[12:15], v[156:159], v[220:223], v[12:15]
	v_mfma_f32_16x16x32_bf16 v[8:11], v[164:167], v[220:223], v[8:11]
	s_waitcnt lgkmcnt(0)
	v_mfma_f32_16x16x32_bf16 v[60:63], v[160:163], v[176:179], v[60:63]
	v_mfma_f32_16x16x32_bf16 v[56:59], v[168:171], v[176:179], v[56:59]
	v_mfma_f32_16x16x32_bf16 v[44:47], v[160:163], v[184:187], v[44:47]
	v_mfma_f32_16x16x32_bf16 v[40:43], v[168:171], v[184:187], v[40:43]
	v_mfma_f32_16x16x32_bf16 v[28:31], v[160:163], v[216:219], v[28:31]
	v_mfma_f32_16x16x32_bf16 v[24:27], v[168:171], v[216:219], v[24:27]
	v_mfma_f32_16x16x32_bf16 v[12:15], v[160:163], v[224:227], v[12:15]
	v_mfma_f32_16x16x32_bf16 v[8:11], v[168:171], v[224:227], v[8:11]
	s_barrier
	s_setprio 1
	s_add_u32 s22, s22, 0x40080
	s_addc_u32 s23, s23, 0
	s_add_i32 s24, s24, s29
	s_mov_b32 m0, s24
	s_nop 0
	global_load_lds_dwordx4 v132, s[22:23]
	s_add_i32 m0, s24, 0x2000
	s_nop 0
	global_load_lds_dwordx4 v128, s[22:23]
	v_add_u32_e32 v168, 0x10000, v154
	ds_read_b128 v[156:159], v168
	ds_read_b128 v[160:163], v168 offset:1024
	ds_read_b128 v[164:167], v168 offset:2048
	ds_read_b128 v[168:171], v168 offset:3072
	s_setprio 0
	s_waitcnt vmcnt(10)
	s_barrier
	v_mfma_f32_16x16x32_bf16 v[52:55], v[228:231], v[172:175], v[52:55]
	v_mfma_f32_16x16x32_bf16 v[48:51], v[236:239], v[172:175], v[48:51]
	v_mfma_f32_16x16x32_bf16 v[36:39], v[228:231], v[180:183], v[36:39]
	v_mfma_f32_16x16x32_bf16 v[32:35], v[236:239], v[180:183], v[32:35]
	v_mfma_f32_16x16x32_bf16 v[20:23], v[228:231], v[188:191], v[20:23]
	v_mfma_f32_16x16x32_bf16 v[16:19], v[236:239], v[188:191], v[16:19]
	v_mfma_f32_16x16x32_bf16 v[4:7], v[228:231], v[220:223], v[4:7]
	v_mfma_f32_16x16x32_bf16 v[0:3], v[236:239], v[220:223], v[0:3]
	v_mfma_f32_16x16x32_bf16 v[52:55], v[232:235], v[176:179], v[52:55]
	v_mfma_f32_16x16x32_bf16 v[48:51], v[240:243], v[176:179], v[48:51]
	v_mfma_f32_16x16x32_bf16 v[36:39], v[232:235], v[184:187], v[36:39]
	v_mfma_f32_16x16x32_bf16 v[32:35], v[240:243], v[184:187], v[32:35]
	v_mfma_f32_16x16x32_bf16 v[20:23], v[232:235], v[216:219], v[20:23]
	v_mfma_f32_16x16x32_bf16 v[16:19], v[240:243], v[216:219], v[16:19]
	v_mfma_f32_16x16x32_bf16 v[4:7], v[232:235], v[224:227], v[4:7]
	v_mfma_f32_16x16x32_bf16 v[0:3], v[240:243], v[224:227], v[0:3]
	s_add_i32 s46, s46, 2
	s_add_u32 s18, s18, 0x100
	s_addc_u32 s19, s19, 0
	s_add_u32 s44, s44, 0x100
	s_addc_u32 s45, s45, 0
	s_cmp_gt_u32 s46, 13
	s_barrier
	s_cbranch_scc0 .LBB0_1104
	s_waitcnt lgkmcnt(0)
	v_mov_b32_e32 v153, v135
	s_mov_b64 s[18:19], s[0:1]
	s_load_dwordx2 s[18:19], s[18:19], 0x88
	s_nop 0
	v_readfirstlane_b32 s7, v153
	s_ashr_i32 s9, s7, 2
	s_lshr_b32 s7, s7, 1
	s_lshl_b32 s22, s41, 7
	s_and_b32 s7, s7, 0x60
	s_andn2_b32 s9, s9, 63
	s_or_b32 s7, s7, s22
	v_lshrrev_b32_e32 v152, 1, v153
	v_and_or_b32 v152, v152, 24, s7
	v_and_or_b32 v153, v153, 15, s9
	v_lshl_add_u32 v156, s16, 8, v153
	v_ashrrev_i32_e32 v153, 31, v152
	v_mov_b32_e32 v168, 0xbfb8aa3b
	v_mov_b32_e32 v169, 0xbfb8aa3b
	v_mov_b32_e32 v170, 1.0
	v_mov_b32_e32 v171, 1.0
	v_pk_mul_f32 v[160:161], v[124:125], v[168:169]
	v_pk_mul_f32 v[162:163], v[126:127], v[168:169]
	v_pk_mul_f32 v[164:165], v[116:117], v[168:169]
	v_pk_mul_f32 v[166:167], v[118:119], v[168:169]
	v_exp_f32_e32 v160, v160
	v_exp_f32_e32 v161, v161
	v_exp_f32_e32 v162, v162
	v_exp_f32_e32 v163, v163
	v_exp_f32_e32 v164, v164
	v_exp_f32_e32 v165, v165
	v_exp_f32_e32 v166, v166
	v_exp_f32_e32 v167, v167
	s_waitcnt lgkmcnt(0)
	v_lshl_add_u64 v[152:153], v[152:153], 1, s[18:19]
	s_mov_b64 s[18:19], 0xa2a4400
	v_lshl_add_u64 v[152:153], v[152:153], 0, s[18:19]
	s_and_b64 vcc, exec, s[4:5]
	s_mov_b32 s41, s6
	s_mov_b32 s16, s8
	s_mov_b64 s[22:23], s[12:13]
	v_pk_add_f32 v[160:161], v[160:161], v[170:171]
	v_pk_add_f32 v[162:163], v[162:163], v[170:171]
	v_pk_add_f32 v[164:165], v[164:165], v[170:171]
	v_pk_add_f32 v[166:167], v[166:167], v[170:171]
	v_rcp_f32_e32 v160, v160
	v_rcp_f32_e32 v161, v161
	v_rcp_f32_e32 v162, v162
	v_rcp_f32_e32 v163, v163
	v_rcp_f32_e32 v164, v164
	v_rcp_f32_e32 v165, v165
	v_rcp_f32_e32 v166, v166
	v_rcp_f32_e32 v167, v167
	v_mov_b32_e32 v158, v156
	v_mad_i64_i32 v[158:159], s[18:19], v158, s73, v[152:153]
	v_pk_mul_f32 v[124:125], v[124:125], v[160:161]
	v_pk_mul_f32 v[126:127], v[126:127], v[162:163]
	v_pk_mul_f32 v[116:117], v[116:117], v[164:165]
	v_pk_mul_f32 v[118:119], v[118:119], v[166:167]
	v_pk_mul_f32 v[120:121], v[120:121], v[124:125]
	v_pk_mul_f32 v[122:123], v[122:123], v[126:127]
	v_pk_mul_f32 v[112:113], v[112:113], v[116:117]
	v_pk_mul_f32 v[114:115], v[114:115], v[118:119]
	v_cvt_pk_bf16_f32 v120, v120, v121
	v_cvt_pk_bf16_f32 v121, v122, v123
	v_cvt_pk_bf16_f32 v122, v112, v113
	v_cvt_pk_bf16_f32 v123, v114, v115
	global_store_dwordx4 v[158:159], v[120:123], off sc1
	v_pk_mul_f32 v[160:161], v[108:109], v[168:169]
	v_pk_mul_f32 v[162:163], v[110:111], v[168:169]
	v_pk_mul_f32 v[164:165], v[100:101], v[168:169]
	v_pk_mul_f32 v[166:167], v[102:103], v[168:169]
	v_exp_f32_e32 v160, v160
	v_exp_f32_e32 v161, v161
	v_exp_f32_e32 v162, v162
	v_exp_f32_e32 v163, v163
	v_exp_f32_e32 v164, v164
	v_exp_f32_e32 v165, v165
	v_exp_f32_e32 v166, v166
	v_exp_f32_e32 v167, v167
	v_pk_add_f32 v[160:161], v[160:161], v[170:171]
	v_pk_add_f32 v[162:163], v[162:163], v[170:171]
	v_pk_add_f32 v[164:165], v[164:165], v[170:171]
	v_pk_add_f32 v[166:167], v[166:167], v[170:171]
	v_rcp_f32_e32 v160, v160
	v_rcp_f32_e32 v161, v161
	v_rcp_f32_e32 v162, v162
	v_rcp_f32_e32 v163, v163
	v_rcp_f32_e32 v164, v164
	v_rcp_f32_e32 v165, v165
	v_rcp_f32_e32 v166, v166
	v_rcp_f32_e32 v167, v167
	v_add_u32_e32 v158, 0x10, v156
	v_mad_i64_i32 v[158:159], s[18:19], v158, s73, v[152:153]
	v_pk_mul_f32 v[108:109], v[108:109], v[160:161]
	v_pk_mul_f32 v[110:111], v[110:111], v[162:163]
	v_pk_mul_f32 v[100:101], v[100:101], v[164:165]
	v_pk_mul_f32 v[102:103], v[102:103], v[166:167]
	v_pk_mul_f32 v[104:105], v[104:105], v[108:109]
	v_pk_mul_f32 v[106:107], v[106:107], v[110:111]
	v_pk_mul_f32 v[96:97], v[96:97], v[100:101]
	v_pk_mul_f32 v[98:99], v[98:99], v[102:103]
	v_cvt_pk_bf16_f32 v104, v104, v105
	v_cvt_pk_bf16_f32 v105, v106, v107
	v_cvt_pk_bf16_f32 v106, v96, v97
	v_cvt_pk_bf16_f32 v107, v98, v99
	global_store_dwordx4 v[158:159], v[104:107], off sc1
	v_pk_mul_f32 v[160:161], v[92:93], v[168:169]
	v_pk_mul_f32 v[162:163], v[94:95], v[168:169]
	v_pk_mul_f32 v[164:165], v[84:85], v[168:169]
	v_pk_mul_f32 v[166:167], v[86:87], v[168:169]
	v_exp_f32_e32 v160, v160
	v_exp_f32_e32 v161, v161
	v_exp_f32_e32 v162, v162
	v_exp_f32_e32 v163, v163
	v_exp_f32_e32 v164, v164
	v_exp_f32_e32 v165, v165
	v_exp_f32_e32 v166, v166
	v_exp_f32_e32 v167, v167
	v_pk_add_f32 v[160:161], v[160:161], v[170:171]
	v_pk_add_f32 v[162:163], v[162:163], v[170:171]
	v_pk_add_f32 v[164:165], v[164:165], v[170:171]
	v_pk_add_f32 v[166:167], v[166:167], v[170:171]
	v_rcp_f32_e32 v160, v160
	v_rcp_f32_e32 v161, v161
	v_rcp_f32_e32 v162, v162
	v_rcp_f32_e32 v163, v163
	v_rcp_f32_e32 v164, v164
	v_rcp_f32_e32 v165, v165
	v_rcp_f32_e32 v166, v166
	v_rcp_f32_e32 v167, v167
	v_add_u32_e32 v158, 0x20, v156
	v_mad_i64_i32 v[158:159], s[18:19], v158, s73, v[152:153]
	v_pk_mul_f32 v[92:93], v[92:93], v[160:161]
	v_pk_mul_f32 v[94:95], v[94:95], v[162:163]
	v_pk_mul_f32 v[84:85], v[84:85], v[164:165]
	v_pk_mul_f32 v[86:87], v[86:87], v[166:167]
	v_pk_mul_f32 v[88:89], v[88:89], v[92:93]
	v_pk_mul_f32 v[90:91], v[90:91], v[94:95]
	v_pk_mul_f32 v[80:81], v[80:81], v[84:85]
	v_pk_mul_f32 v[82:83], v[82:83], v[86:87]
	v_cvt_pk_bf16_f32 v88, v88, v89
	v_cvt_pk_bf16_f32 v89, v90, v91
	v_cvt_pk_bf16_f32 v90, v80, v81
	v_cvt_pk_bf16_f32 v91, v82, v83
	global_store_dwordx4 v[158:159], v[88:91], off sc1
	v_pk_mul_f32 v[160:161], v[76:77], v[168:169]
	v_pk_mul_f32 v[162:163], v[78:79], v[168:169]
	v_pk_mul_f32 v[164:165], v[68:69], v[168:169]
	v_pk_mul_f32 v[166:167], v[70:71], v[168:169]
	v_exp_f32_e32 v160, v160
	v_exp_f32_e32 v161, v161
	v_exp_f32_e32 v162, v162
	v_exp_f32_e32 v163, v163
	v_exp_f32_e32 v164, v164
	v_exp_f32_e32 v165, v165
	v_exp_f32_e32 v166, v166
	v_exp_f32_e32 v167, v167
	v_pk_add_f32 v[160:161], v[160:161], v[170:171]
	v_pk_add_f32 v[162:163], v[162:163], v[170:171]
	v_pk_add_f32 v[164:165], v[164:165], v[170:171]
	v_pk_add_f32 v[166:167], v[166:167], v[170:171]
	v_rcp_f32_e32 v160, v160
	v_rcp_f32_e32 v161, v161
	v_rcp_f32_e32 v162, v162
	v_rcp_f32_e32 v163, v163
	v_rcp_f32_e32 v164, v164
	v_rcp_f32_e32 v165, v165
	v_rcp_f32_e32 v166, v166
	v_rcp_f32_e32 v167, v167
	v_add_u32_e32 v158, 0x30, v156
	v_mad_i64_i32 v[158:159], s[18:19], v158, s73, v[152:153]
	v_pk_mul_f32 v[76:77], v[76:77], v[160:161]
	v_pk_mul_f32 v[78:79], v[78:79], v[162:163]
	v_pk_mul_f32 v[68:69], v[68:69], v[164:165]
	v_pk_mul_f32 v[70:71], v[70:71], v[166:167]
	v_pk_mul_f32 v[72:73], v[72:73], v[76:77]
	v_pk_mul_f32 v[74:75], v[74:75], v[78:79]
	v_pk_mul_f32 v[64:65], v[64:65], v[68:69]
	v_pk_mul_f32 v[66:67], v[66:67], v[70:71]
	v_cvt_pk_bf16_f32 v72, v72, v73
	v_cvt_pk_bf16_f32 v73, v74, v75
	v_cvt_pk_bf16_f32 v74, v64, v65
	v_cvt_pk_bf16_f32 v75, v66, v67
	global_store_dwordx4 v[158:159], v[72:75], off sc1
	v_pk_mul_f32 v[160:161], v[60:61], v[168:169]
	v_pk_mul_f32 v[162:163], v[62:63], v[168:169]
	v_pk_mul_f32 v[164:165], v[52:53], v[168:169]
	v_pk_mul_f32 v[166:167], v[54:55], v[168:169]
	v_exp_f32_e32 v160, v160
	v_exp_f32_e32 v161, v161
	v_exp_f32_e32 v162, v162
	v_exp_f32_e32 v163, v163
	v_exp_f32_e32 v164, v164
	v_exp_f32_e32 v165, v165
	v_exp_f32_e32 v166, v166
	v_exp_f32_e32 v167, v167
	v_pk_add_f32 v[160:161], v[160:161], v[170:171]
	v_pk_add_f32 v[162:163], v[162:163], v[170:171]
	v_pk_add_f32 v[164:165], v[164:165], v[170:171]
	v_pk_add_f32 v[166:167], v[166:167], v[170:171]
	v_rcp_f32_e32 v160, v160
	v_rcp_f32_e32 v161, v161
	v_rcp_f32_e32 v162, v162
	v_rcp_f32_e32 v163, v163
	v_rcp_f32_e32 v164, v164
	v_rcp_f32_e32 v165, v165
	v_rcp_f32_e32 v166, v166
	v_rcp_f32_e32 v167, v167
	v_add_u32_e32 v158, 0x80, v156
	v_mad_i64_i32 v[158:159], s[18:19], v158, s73, v[152:153]
	v_pk_mul_f32 v[60:61], v[60:61], v[160:161]
	v_pk_mul_f32 v[62:63], v[62:63], v[162:163]
	v_pk_mul_f32 v[52:53], v[52:53], v[164:165]
	v_pk_mul_f32 v[54:55], v[54:55], v[166:167]
	v_pk_mul_f32 v[56:57], v[56:57], v[60:61]
	v_pk_mul_f32 v[58:59], v[58:59], v[62:63]
	v_pk_mul_f32 v[48:49], v[48:49], v[52:53]
	v_pk_mul_f32 v[50:51], v[50:51], v[54:55]
	v_cvt_pk_bf16_f32 v56, v56, v57
	v_cvt_pk_bf16_f32 v57, v58, v59
	v_cvt_pk_bf16_f32 v58, v48, v49
	v_cvt_pk_bf16_f32 v59, v50, v51
	global_store_dwordx4 v[158:159], v[56:59], off sc1
	v_pk_mul_f32 v[160:161], v[44:45], v[168:169]
	v_pk_mul_f32 v[162:163], v[46:47], v[168:169]
	v_pk_mul_f32 v[164:165], v[36:37], v[168:169]
	v_pk_mul_f32 v[166:167], v[38:39], v[168:169]
	v_exp_f32_e32 v160, v160
	v_exp_f32_e32 v161, v161
	v_exp_f32_e32 v162, v162
	v_exp_f32_e32 v163, v163
	v_exp_f32_e32 v164, v164
	v_exp_f32_e32 v165, v165
	v_exp_f32_e32 v166, v166
	v_exp_f32_e32 v167, v167
	v_pk_add_f32 v[160:161], v[160:161], v[170:171]
	v_pk_add_f32 v[162:163], v[162:163], v[170:171]
	v_pk_add_f32 v[164:165], v[164:165], v[170:171]
	v_pk_add_f32 v[166:167], v[166:167], v[170:171]
	v_rcp_f32_e32 v160, v160
	v_rcp_f32_e32 v161, v161
	v_rcp_f32_e32 v162, v162
	v_rcp_f32_e32 v163, v163
	v_rcp_f32_e32 v164, v164
	v_rcp_f32_e32 v165, v165
	v_rcp_f32_e32 v166, v166
	v_rcp_f32_e32 v167, v167
	v_add_u32_e32 v158, 0x90, v156
	v_mad_i64_i32 v[158:159], s[18:19], v158, s73, v[152:153]
	v_pk_mul_f32 v[44:45], v[44:45], v[160:161]
	v_pk_mul_f32 v[46:47], v[46:47], v[162:163]
	v_pk_mul_f32 v[36:37], v[36:37], v[164:165]
	v_pk_mul_f32 v[38:39], v[38:39], v[166:167]
	v_pk_mul_f32 v[40:41], v[40:41], v[44:45]
	v_pk_mul_f32 v[42:43], v[42:43], v[46:47]
	v_pk_mul_f32 v[32:33], v[32:33], v[36:37]
	v_pk_mul_f32 v[34:35], v[34:35], v[38:39]
	v_cvt_pk_bf16_f32 v40, v40, v41
	v_cvt_pk_bf16_f32 v41, v42, v43
	v_cvt_pk_bf16_f32 v42, v32, v33
	v_cvt_pk_bf16_f32 v43, v34, v35
	global_store_dwordx4 v[158:159], v[40:43], off sc1
	v_pk_mul_f32 v[160:161], v[28:29], v[168:169]
	v_pk_mul_f32 v[162:163], v[30:31], v[168:169]
	v_pk_mul_f32 v[164:165], v[20:21], v[168:169]
	v_pk_mul_f32 v[166:167], v[22:23], v[168:169]
	v_exp_f32_e32 v160, v160
	v_exp_f32_e32 v161, v161
	v_exp_f32_e32 v162, v162
	v_exp_f32_e32 v163, v163
	v_exp_f32_e32 v164, v164
	v_exp_f32_e32 v165, v165
	v_exp_f32_e32 v166, v166
	v_exp_f32_e32 v167, v167
	v_pk_add_f32 v[160:161], v[160:161], v[170:171]
	v_pk_add_f32 v[162:163], v[162:163], v[170:171]
	v_pk_add_f32 v[164:165], v[164:165], v[170:171]
	v_pk_add_f32 v[166:167], v[166:167], v[170:171]
	v_rcp_f32_e32 v160, v160
	v_rcp_f32_e32 v161, v161
	v_rcp_f32_e32 v162, v162
	v_rcp_f32_e32 v163, v163
	v_rcp_f32_e32 v164, v164
	v_rcp_f32_e32 v165, v165
	v_rcp_f32_e32 v166, v166
	v_rcp_f32_e32 v167, v167
	v_add_u32_e32 v158, 0xa0, v156
	v_mad_i64_i32 v[158:159], s[18:19], v158, s73, v[152:153]
	v_pk_mul_f32 v[28:29], v[28:29], v[160:161]
	v_pk_mul_f32 v[30:31], v[30:31], v[162:163]
	v_pk_mul_f32 v[20:21], v[20:21], v[164:165]
	v_pk_mul_f32 v[22:23], v[22:23], v[166:167]
	v_pk_mul_f32 v[24:25], v[24:25], v[28:29]
	v_pk_mul_f32 v[26:27], v[26:27], v[30:31]
	v_pk_mul_f32 v[16:17], v[16:17], v[20:21]
	v_pk_mul_f32 v[18:19], v[18:19], v[22:23]
	v_cvt_pk_bf16_f32 v24, v24, v25
	v_cvt_pk_bf16_f32 v25, v26, v27
	v_cvt_pk_bf16_f32 v26, v16, v17
	v_cvt_pk_bf16_f32 v27, v18, v19
	global_store_dwordx4 v[158:159], v[24:27], off sc1
	v_pk_mul_f32 v[160:161], v[12:13], v[168:169]
	v_pk_mul_f32 v[162:163], v[14:15], v[168:169]
	v_pk_mul_f32 v[164:165], v[4:5], v[168:169]
	v_pk_mul_f32 v[166:167], v[6:7], v[168:169]
	v_exp_f32_e32 v160, v160
	v_exp_f32_e32 v161, v161
	v_exp_f32_e32 v162, v162
	v_exp_f32_e32 v163, v163
	v_exp_f32_e32 v164, v164
	v_exp_f32_e32 v165, v165
	v_exp_f32_e32 v166, v166
	v_exp_f32_e32 v167, v167
	v_pk_add_f32 v[160:161], v[160:161], v[170:171]
	v_pk_add_f32 v[162:163], v[162:163], v[170:171]
	v_pk_add_f32 v[164:165], v[164:165], v[170:171]
	v_pk_add_f32 v[166:167], v[166:167], v[170:171]
	v_rcp_f32_e32 v160, v160
	v_rcp_f32_e32 v161, v161
	v_rcp_f32_e32 v162, v162
	v_rcp_f32_e32 v163, v163
	v_rcp_f32_e32 v164, v164
	v_rcp_f32_e32 v165, v165
	v_rcp_f32_e32 v166, v166
	v_rcp_f32_e32 v167, v167
	v_add_u32_e32 v158, 0xb0, v156
	v_mad_i64_i32 v[158:159], s[18:19], v158, s73, v[152:153]
	v_pk_mul_f32 v[12:13], v[12:13], v[160:161]
	v_pk_mul_f32 v[14:15], v[14:15], v[162:163]
	v_pk_mul_f32 v[4:5], v[4:5], v[164:165]
	v_pk_mul_f32 v[6:7], v[6:7], v[166:167]
	v_pk_mul_f32 v[8:9], v[8:9], v[12:13]
	v_pk_mul_f32 v[10:11], v[10:11], v[14:15]
	v_pk_mul_f32 v[0:1], v[0:1], v[4:5]
	v_pk_mul_f32 v[2:3], v[2:3], v[6:7]
	v_cvt_pk_bf16_f32 v8, v8, v9
	v_cvt_pk_bf16_f32 v9, v10, v11
	v_cvt_pk_bf16_f32 v10, v0, v1
	v_cvt_pk_bf16_f32 v11, v2, v3
	global_store_dwordx4 v[158:159], v[8:11], off sc1
	s_mov_b64 s[18:19], s[10:11]
	s_cbranch_vccz .LBB0_1101
	s_waitcnt vmcnt(0)
	s_cmpk_gt_u32 s14, 0xff
	s_cbranch_scc1 .LBB0_1108
	s_barrier

.LBB0_1234:
	s_add_i32 s40, s10, 2
	s_add_u32 s12, s8, 0x80
	s_addc_u32 s11, s9, 0
	s_add_i32 s41, 0, 0x10000
	s_cmp_eq_u32 s29, s10
	s_cselect_b32 s10, s2, s12
	s_cselect_b32 s11, s3, s11
	s_cselect_b32 s13, s7, s39
	s_cselect_b32 s12, s6, s38
	s_add_i32 m0, s22, 0xc000
	ds_read_b128 v[172:175], v155
	ds_read_b128 v[180:183], v155 offset:2048
	ds_read_b128 v[188:191], v155 offset:4096
	ds_read_b128 v[220:223], v155 offset:6144
	ds_read_b128 v[176:179], v155 offset:1024
	ds_read_b128 v[184:187], v155 offset:3072
	ds_read_b128 v[216:219], v155 offset:5120
	ds_read_b128 v[224:227], v155 offset:7168
	global_load_lds_dwordx4 v130, s[8:9]
	s_add_i32 m0, s22, 0xe000
	s_nop 0
	global_load_lds_dwordx4 v150, s[8:9]
	s_waitcnt lgkmcnt(8)
	s_setprio 0
	s_waitcnt vmcnt(10)
	s_barrier
	s_waitcnt lgkmcnt(4)
	v_mfma_f32_16x16x32_bf16 v[124:127], v[156:159], v[172:175], v[124:127]
	v_mfma_f32_16x16x32_bf16 v[120:123], v[164:167], v[172:175], v[120:123]
	v_mfma_f32_16x16x32_bf16 v[116:119], v[156:159], v[180:183], v[116:119]
	v_mfma_f32_16x16x32_bf16 v[108:111], v[164:167], v[180:183], v[108:111]
	v_mfma_f32_16x16x32_bf16 v[100:103], v[156:159], v[188:191], v[100:103]
	v_mfma_f32_16x16x32_bf16 v[92:95], v[164:167], v[188:191], v[92:95]
	v_mfma_f32_16x16x32_bf16 v[84:87], v[156:159], v[220:223], v[84:87]
	v_mfma_f32_16x16x32_bf16 v[76:79], v[164:167], v[220:223], v[76:79]
	s_waitcnt lgkmcnt(0)
	v_mfma_f32_16x16x32_bf16 v[124:127], v[160:163], v[176:179], v[124:127]
	v_mfma_f32_16x16x32_bf16 v[120:123], v[168:171], v[176:179], v[120:123]
	v_mfma_f32_16x16x32_bf16 v[116:119], v[160:163], v[184:187], v[116:119]
	v_mfma_f32_16x16x32_bf16 v[108:111], v[168:171], v[184:187], v[108:111]
	v_mfma_f32_16x16x32_bf16 v[100:103], v[160:163], v[216:219], v[100:103]
	v_mfma_f32_16x16x32_bf16 v[92:95], v[168:171], v[216:219], v[92:95]
	v_mfma_f32_16x16x32_bf16 v[84:87], v[160:163], v[224:227], v[84:87]
	v_mfma_f32_16x16x32_bf16 v[76:79], v[168:171], v[224:227], v[76:79]
	s_barrier
	s_setprio 1
	s_add_i32 s42, 0, 0x14000
	v_add_u32_e32 v152, s42, v154
	s_add_i32 s41, s41, s19
	ds_read_b128 v[228:231], v152
	ds_read_b128 v[236:239], v152 offset:2048
	ds_read_b128 v[232:235], v152 offset:1024
	ds_read_b128 v[240:243], v152 offset:3072
	v_lshl_add_u64 v[152:153], s[12:13], 0, v[132:133]
	s_mov_b32 m0, s41
	v_lshl_add_u64 v[244:245], s[12:13], 0, v[128:129]
	global_load_lds_dwordx4 v132, s[12:13]
	s_add_i32 m0, s41, 0x2000
	s_nop 0
	global_load_lds_dwordx4 v128, s[12:13]
	s_setprio 0
	s_waitcnt vmcnt(10)
	s_barrier
	s_waitcnt lgkmcnt(2)
	v_mfma_f32_16x16x32_bf16 v[112:115], v[228:231], v[172:175], v[112:115]
	v_mfma_f32_16x16x32_bf16 v[104:107], v[236:239], v[172:175], v[104:107]
	v_mfma_f32_16x16x32_bf16 v[96:99], v[228:231], v[180:183], v[96:99]
	v_mfma_f32_16x16x32_bf16 v[88:91], v[236:239], v[180:183], v[88:91]
	v_mfma_f32_16x16x32_bf16 v[80:83], v[228:231], v[188:191], v[80:83]
	v_mfma_f32_16x16x32_bf16 v[72:75], v[236:239], v[188:191], v[72:75]
	v_mfma_f32_16x16x32_bf16 v[68:71], v[228:231], v[220:223], v[68:71]
	v_mfma_f32_16x16x32_bf16 v[64:67], v[236:239], v[220:223], v[64:67]
	s_waitcnt lgkmcnt(0)
	v_mfma_f32_16x16x32_bf16 v[112:115], v[232:235], v[176:179], v[112:115]
	v_mfma_f32_16x16x32_bf16 v[104:107], v[240:243], v[176:179], v[104:107]
	v_mfma_f32_16x16x32_bf16 v[96:99], v[232:235], v[184:187], v[96:99]
	v_mfma_f32_16x16x32_bf16 v[88:91], v[240:243], v[184:187], v[88:91]
	v_mfma_f32_16x16x32_bf16 v[80:83], v[232:235], v[216:219], v[80:83]
	v_mfma_f32_16x16x32_bf16 v[72:75], v[240:243], v[216:219], v[72:75]
	v_mfma_f32_16x16x32_bf16 v[68:71], v[232:235], v[224:227], v[68:71]
	v_mfma_f32_16x16x32_bf16 v[64:67], v[240:243], v[224:227], v[64:67]
	s_mov_b32 m0, s22
	v_lshl_add_u64 v[246:247], s[10:11], 0, v[132:133]
	s_barrier
	ds_read_b128 v[172:175], v155 offset:16384
	ds_read_b128 v[180:183], v155 offset:18432
	ds_read_b128 v[188:191], v155 offset:20480
	ds_read_b128 v[220:223], v155 offset:22528
	ds_read_b128 v[176:179], v155 offset:17408
	ds_read_b128 v[184:187], v155 offset:19456
	ds_read_b128 v[216:219], v155 offset:21504
	ds_read_b128 v[224:227], v155 offset:23552
	global_load_lds_dwordx4 v132, s[10:11]
	v_lshl_add_u64 v[248:249], s[10:11], 0, v[128:129]
	s_mov_b32 m0, s23
	s_nop 0
	global_load_lds_dwordx4 v128, s[10:11]
	s_setprio 0
	s_waitcnt vmcnt(10)
	s_barrier
	s_waitcnt lgkmcnt(4)
	v_mfma_f32_16x16x32_bf16 v[60:63], v[156:159], v[172:175], v[60:63]
	v_mfma_f32_16x16x32_bf16 v[56:59], v[164:167], v[172:175], v[56:59]
	v_mfma_f32_16x16x32_bf16 v[52:55], v[156:159], v[180:183], v[52:55]
	v_mfma_f32_16x16x32_bf16 v[44:47], v[164:167], v[180:183], v[44:47]
	v_mfma_f32_16x16x32_bf16 v[36:39], v[156:159], v[188:191], v[36:39]
	v_mfma_f32_16x16x32_bf16 v[28:31], v[164:167], v[188:191], v[28:31]
	v_mfma_f32_16x16x32_bf16 v[20:23], v[156:159], v[220:223], v[20:23]
	v_mfma_f32_16x16x32_bf16 v[12:15], v[164:167], v[220:223], v[12:15]
	s_waitcnt lgkmcnt(0)
	v_mfma_f32_16x16x32_bf16 v[60:63], v[160:163], v[176:179], v[60:63]
	v_mfma_f32_16x16x32_bf16 v[56:59], v[168:171], v[176:179], v[56:59]
	v_mfma_f32_16x16x32_bf16 v[52:55], v[160:163], v[184:187], v[52:55]
	v_mfma_f32_16x16x32_bf16 v[44:47], v[168:171], v[184:187], v[44:47]
	v_mfma_f32_16x16x32_bf16 v[36:39], v[160:163], v[216:219], v[36:39]
	v_mfma_f32_16x16x32_bf16 v[28:31], v[168:171], v[216:219], v[28:31]
	v_mfma_f32_16x16x32_bf16 v[20:23], v[160:163], v[224:227], v[20:23]
	v_mfma_f32_16x16x32_bf16 v[12:15], v[168:171], v[224:227], v[12:15]
	s_barrier
	s_setprio 1
	s_add_u32 s12, s12, s58
	s_addc_u32 s13, s13, 0
	s_add_i32 s41, s42, s19
	v_lshl_add_u64 v[250:251], s[12:13], 0, v[132:133]
	s_mov_b32 m0, s41
	v_lshl_add_u64 v[252:253], s[12:13], 0, v[128:129]
	global_load_lds_dwordx4 v132, s[12:13]
	s_add_i32 m0, s41, 0x2000
	s_nop 0
	global_load_lds_dwordx4 v128, s[12:13]
	v_add_u32_e32 v168, 0x18000, v154
	ds_read_b128 v[156:159], v168
	ds_read_b128 v[160:163], v168 offset:1024
	ds_read_b128 v[164:167], v168 offset:2048
	ds_read_b128 v[168:171], v168 offset:3072
	s_setprio 0
	s_waitcnt vmcnt(10)
	s_barrier
	v_mfma_f32_16x16x32_bf16 v[48:51], v[228:231], v[172:175], v[48:51]
	v_mfma_f32_16x16x32_bf16 v[40:43], v[236:239], v[172:175], v[40:43]
	v_mfma_f32_16x16x32_bf16 v[32:35], v[228:231], v[180:183], v[32:35]
	v_mfma_f32_16x16x32_bf16 v[24:27], v[236:239], v[180:183], v[24:27]
	v_mfma_f32_16x16x32_bf16 v[16:19], v[228:231], v[188:191], v[16:19]
	v_mfma_f32_16x16x32_bf16 v[8:11], v[236:239], v[188:191], v[8:11]
	v_mfma_f32_16x16x32_bf16 v[4:7], v[228:231], v[220:223], v[4:7]
	v_mfma_f32_16x16x32_bf16 v[0:3], v[236:239], v[220:223], v[0:3]
	v_mfma_f32_16x16x32_bf16 v[48:51], v[232:235], v[176:179], v[48:51]
	v_mfma_f32_16x16x32_bf16 v[40:43], v[240:243], v[176:179], v[40:43]
	v_mfma_f32_16x16x32_bf16 v[32:35], v[232:235], v[184:187], v[32:35]
	v_mfma_f32_16x16x32_bf16 v[24:27], v[240:243], v[184:187], v[24:27]
	v_mfma_f32_16x16x32_bf16 v[16:19], v[232:235], v[216:219], v[16:19]
	v_mfma_f32_16x16x32_bf16 v[8:11], v[240:243], v[216:219], v[8:11]
	v_mfma_f32_16x16x32_bf16 v[4:7], v[232:235], v[224:227], v[4:7]
	v_mfma_f32_16x16x32_bf16 v[0:3], v[240:243], v[224:227], v[0:3]
	s_add_i32 s12, 0, 0x18000
	s_barrier
	s_add_u32 s10, s10, s58
	s_addc_u32 s11, s11, 0
	s_mov_b32 m0, s24
	ds_read_b128 v[172:175], v155 offset:32768
	ds_read_b128 v[180:183], v155 offset:34816
	ds_read_b128 v[188:191], v155 offset:36864
	ds_read_b128 v[220:223], v155 offset:38912
	ds_read_b128 v[176:179], v155 offset:33792
	ds_read_b128 v[184:187], v155 offset:35840
	ds_read_b128 v[216:219], v155 offset:37888
	ds_read_b128 v[224:227], v155 offset:39936
	global_load_lds_dwordx4 v132, s[10:11]
	s_mov_b32 m0, s25
	s_nop 0
	global_load_lds_dwordx4 v128, s[10:11]
	s_waitcnt lgkmcnt(8)
	s_setprio 0
	s_waitcnt vmcnt(10)
	s_barrier
	s_waitcnt lgkmcnt(4)
	v_mfma_f32_16x16x32_bf16 v[124:127], v[156:159], v[172:175], v[124:127]
	v_mfma_f32_16x16x32_bf16 v[120:123], v[164:167], v[172:175], v[120:123]
	v_mfma_f32_16x16x32_bf16 v[116:119], v[156:159], v[180:183], v[116:119]
	v_mfma_f32_16x16x32_bf16 v[108:111], v[164:167], v[180:183], v[108:111]
	v_mfma_f32_16x16x32_bf16 v[100:103], v[156:159], v[188:191], v[100:103]
	v_mfma_f32_16x16x32_bf16 v[92:95], v[164:167], v[188:191], v[92:95]
	v_mfma_f32_16x16x32_bf16 v[84:87], v[156:159], v[220:223], v[84:87]
	v_mfma_f32_16x16x32_bf16 v[76:79], v[164:167], v[220:223], v[76:79]
	s_waitcnt lgkmcnt(0)
	v_mfma_f32_16x16x32_bf16 v[124:127], v[160:163], v[176:179], v[124:127]
	v_mfma_f32_16x16x32_bf16 v[120:123], v[168:171], v[176:179], v[120:123]
	v_mfma_f32_16x16x32_bf16 v[116:119], v[160:163], v[184:187], v[116:119]
	v_mfma_f32_16x16x32_bf16 v[108:111], v[168:171], v[184:187], v[108:111]
	v_mfma_f32_16x16x32_bf16 v[100:103], v[160:163], v[216:219], v[100:103]
	v_mfma_f32_16x16x32_bf16 v[92:95], v[168:171], v[216:219], v[92:95]
	v_mfma_f32_16x16x32_bf16 v[84:87], v[160:163], v[224:227], v[84:87]
	v_mfma_f32_16x16x32_bf16 v[76:79], v[168:171], v[224:227], v[76:79]
	s_barrier
	s_setprio 1
	s_add_i32 s10, 0, 0x1c000
	s_add_i32 s11, s12, s19
	v_add_u32_e32 v200, s10, v154
	v_lshl_add_u64 v[152:153], v[152:153], 0, s[66:67]
	s_mov_b32 m0, s11
	ds_read_b128 v[228:231], v200
	ds_read_b128 v[236:239], v200 offset:2048
	ds_read_b128 v[232:235], v200 offset:1024
	ds_read_b128 v[240:243], v200 offset:3072
	global_load_lds_dwordx4 v[152:153], off
	v_lshl_add_u64 v[152:153], v[244:245], 0, s[66:67]
	s_add_i32 m0, s11, 0x2000
	s_nop 0
	global_load_lds_dwordx4 v[152:153], off
	s_setprio 0
	s_waitcnt vmcnt(10)
	s_barrier
	s_waitcnt lgkmcnt(2)
	v_mfma_f32_16x16x32_bf16 v[112:115], v[228:231], v[172:175], v[112:115]
	v_mfma_f32_16x16x32_bf16 v[104:107], v[236:239], v[172:175], v[104:107]
	v_mfma_f32_16x16x32_bf16 v[96:99], v[228:231], v[180:183], v[96:99]
	v_mfma_f32_16x16x32_bf16 v[88:91], v[236:239], v[180:183], v[88:91]
	v_mfma_f32_16x16x32_bf16 v[80:83], v[228:231], v[188:191], v[80:83]
	v_mfma_f32_16x16x32_bf16 v[72:75], v[236:239], v[188:191], v[72:75]
	v_mfma_f32_16x16x32_bf16 v[68:71], v[228:231], v[220:223], v[68:71]
	v_mfma_f32_16x16x32_bf16 v[64:67], v[236:239], v[220:223], v[64:67]
	s_waitcnt lgkmcnt(0)
	v_mfma_f32_16x16x32_bf16 v[112:115], v[232:235], v[176:179], v[112:115]
	v_mfma_f32_16x16x32_bf16 v[104:107], v[240:243], v[176:179], v[104:107]
	v_mfma_f32_16x16x32_bf16 v[96:99], v[232:235], v[184:187], v[96:99]
	v_mfma_f32_16x16x32_bf16 v[88:91], v[240:243], v[184:187], v[88:91]
	v_mfma_f32_16x16x32_bf16 v[80:83], v[232:235], v[216:219], v[80:83]
	v_mfma_f32_16x16x32_bf16 v[72:75], v[240:243], v[216:219], v[72:75]
	v_mfma_f32_16x16x32_bf16 v[68:71], v[232:235], v[224:227], v[68:71]
	v_mfma_f32_16x16x32_bf16 v[64:67], v[240:243], v[224:227], v[64:67]
	s_mov_b32 m0, s26
	v_lshl_add_u64 v[152:153], v[246:247], 0, s[66:67]
	s_barrier
	ds_read_b128 v[172:175], v155 offset:49152
	ds_read_b128 v[180:183], v155 offset:51200
	ds_read_b128 v[188:191], v155 offset:53248
	ds_read_b128 v[220:223], v155 offset:55296
	ds_read_b128 v[176:179], v155 offset:50176
	ds_read_b128 v[184:187], v155 offset:52224
	ds_read_b128 v[216:219], v155 offset:54272
	ds_read_b128 v[224:227], v155 offset:56320
	global_load_lds_dwordx4 v[152:153], off
	v_lshl_add_u64 v[152:153], v[248:249], 0, s[66:67]
	s_mov_b32 m0, s27
	s_nop 0
	global_load_lds_dwordx4 v[152:153], off
	s_setprio 0
	s_waitcnt vmcnt(10)
	s_barrier
	s_waitcnt lgkmcnt(4)
	v_mfma_f32_16x16x32_bf16 v[60:63], v[156:159], v[172:175], v[60:63]
	v_mfma_f32_16x16x32_bf16 v[56:59], v[164:167], v[172:175], v[56:59]
	v_mfma_f32_16x16x32_bf16 v[52:55], v[156:159], v[180:183], v[52:55]
	v_mfma_f32_16x16x32_bf16 v[44:47], v[164:167], v[180:183], v[44:47]
	v_mfma_f32_16x16x32_bf16 v[36:39], v[156:159], v[188:191], v[36:39]
	v_mfma_f32_16x16x32_bf16 v[28:31], v[164:167], v[188:191], v[28:31]
	v_mfma_f32_16x16x32_bf16 v[20:23], v[156:159], v[220:223], v[20:23]
	v_mfma_f32_16x16x32_bf16 v[12:15], v[164:167], v[220:223], v[12:15]
	s_waitcnt lgkmcnt(0)
	v_mfma_f32_16x16x32_bf16 v[60:63], v[160:163], v[176:179], v[60:63]
	v_mfma_f32_16x16x32_bf16 v[56:59], v[168:171], v[176:179], v[56:59]
	v_mfma_f32_16x16x32_bf16 v[52:55], v[160:163], v[184:187], v[52:55]
	v_mfma_f32_16x16x32_bf16 v[44:47], v[168:171], v[184:187], v[44:47]
	v_mfma_f32_16x16x32_bf16 v[36:39], v[160:163], v[216:219], v[36:39]
	v_mfma_f32_16x16x32_bf16 v[28:31], v[168:171], v[216:219], v[28:31]
	v_mfma_f32_16x16x32_bf16 v[20:23], v[160:163], v[224:227], v[20:23]
	v_mfma_f32_16x16x32_bf16 v[12:15], v[168:171], v[224:227], v[12:15]
	s_barrier
	s_setprio 1
	s_add_i32 s10, s10, s19
	v_lshl_add_u64 v[152:153], v[250:251], 0, s[66:67]
	s_mov_b32 m0, s10
	s_nop 0
	global_load_lds_dwordx4 v[152:153], off
	v_lshl_add_u64 v[152:153], v[252:253], 0, s[66:67]
	s_add_i32 m0, s10, 0x2000
	s_nop 0
	global_load_lds_dwordx4 v[152:153], off
	v_add_u32_e32 v168, 0x10000, v154
	ds_read_b128 v[156:159], v168
	ds_read_b128 v[160:163], v168 offset:1024
	ds_read_b128 v[164:167], v168 offset:2048
	ds_read_b128 v[168:171], v168 offset:3072
	s_setprio 0
	s_waitcnt vmcnt(10)
	s_barrier
	v_mfma_f32_16x16x32_bf16 v[48:51], v[228:231], v[172:175], v[48:51]
	v_mfma_f32_16x16x32_bf16 v[40:43], v[236:239], v[172:175], v[40:43]
	v_mfma_f32_16x16x32_bf16 v[32:35], v[228:231], v[180:183], v[32:35]
	v_mfma_f32_16x16x32_bf16 v[24:27], v[236:239], v[180:183], v[24:27]
	v_mfma_f32_16x16x32_bf16 v[16:19], v[228:231], v[188:191], v[16:19]
	v_mfma_f32_16x16x32_bf16 v[8:11], v[236:239], v[188:191], v[8:11]
	v_mfma_f32_16x16x32_bf16 v[4:7], v[228:231], v[220:223], v[4:7]
	v_mfma_f32_16x16x32_bf16 v[0:3], v[236:239], v[220:223], v[0:3]
	v_mfma_f32_16x16x32_bf16 v[48:51], v[232:235], v[176:179], v[48:51]
	v_mfma_f32_16x16x32_bf16 v[40:43], v[240:243], v[176:179], v[40:43]
	v_mfma_f32_16x16x32_bf16 v[32:35], v[232:235], v[184:187], v[32:35]
	v_mfma_f32_16x16x32_bf16 v[24:27], v[240:243], v[184:187], v[24:27]
	v_mfma_f32_16x16x32_bf16 v[16:19], v[232:235], v[216:219], v[16:19]
	v_mfma_f32_16x16x32_bf16 v[8:11], v[240:243], v[216:219], v[8:11]
	v_mfma_f32_16x16x32_bf16 v[4:7], v[232:235], v[224:227], v[4:7]
	v_mfma_f32_16x16x32_bf16 v[0:3], v[240:243], v[224:227], v[0:3]
	s_add_u32 s8, s8, 0x100
	s_addc_u32 s9, s9, 0
	s_add_u32 s38, s38, 0x100
	s_addc_u32 s39, s39, 0
	s_cmp_ge_u32 s40, s28
	s_mov_b32 s10, s40
	s_barrier
	s_cbranch_scc0 .LBB0_1234
	s_waitcnt lgkmcnt(0)
	v_mov_b32_e32 v152, v135
	s_mov_b64 s[8:9], s[0:1]
	v_readfirstlane_b32 s10, v152
	s_ashr_i32 s12, s10, 2
	s_load_dwordx2 s[8:9], s[8:9], 0x88
	s_lshl_b32 s11, s36, 8
	s_andn2_b32 s12, s12, 63
	s_lshr_b32 s10, s10, 1
	s_add_i32 s12, s12, s11
	s_lshl_b32 s11, s37, 8
	s_and_b32 s10, s10, 0x60
	v_and_or_b32 v156, v152, 15, s12
	s_or_b32 s10, s10, s11
	v_lshrrev_b32_e32 v152, 1, v152
	v_and_or_b32 v152, v152, 24, s10
	v_ashrrev_i32_e32 v153, 31, v152
	s_waitcnt lgkmcnt(0)
	v_lshl_add_u64 v[152:153], v[152:153], 1, s[8:9]
	s_mov_b64 s[8:9], 0x62a4400
	v_ashrrev_i32_e32 v157, 31, v156
	v_lshl_add_u64 v[158:159], v[152:153], 0, s[8:9]
	v_lshlrev_b64 v[152:153], 11, v[156:157]
	v_lshl_add_u64 v[152:153], v[158:159], 0, v[152:153]
	s_mov_b64 s[8:9], 0x40000
	v_cvt_pk_bf16_f32 v68, v68, v69
	v_cvt_pk_bf16_f32 v69, v70, v71
	v_cvt_pk_bf16_f32 v70, v64, v65
	v_lshl_add_u64 v[64:65], v[152:153], 0, s[8:9]
	s_mov_b32 s8, 0x40000
	v_cvt_pk_bf16_f32 v60, v60, v61
	v_cvt_pk_bf16_f32 v61, v62, v63
	v_cvt_pk_bf16_f32 v62, v56, v57
	v_add_co_u32_e32 v56, vcc, s8, v152
	v_cvt_pk_bf16_f32 v48, v48, v49
	v_cvt_pk_bf16_f32 v49, v50, v51
	s_mov_b64 s[8:9], 0x48000
	s_nop 0
	v_addc_co_u32_e32 v57, vcc, 0, v153, vcc
	v_cvt_pk_bf16_f32 v50, v40, v41
	v_cvt_pk_bf16_f32 v51, v42, v43
	global_store_dwordx4 v[64:65], v[48:51], off offset:256 sc1
	v_cvt_pk_bf16_f32 v42, v44, v45
	v_cvt_pk_bf16_f32 v32, v32, v33
	v_cvt_pk_bf16_f32 v33, v34, v35
	v_cvt_pk_bf16_f32 v112, v112, v113
	v_cvt_pk_bf16_f32 v113, v114, v115
	s_nop 1
	v_lshl_add_u64 v[48:49], v[152:153], 0, s[8:9]
	s_mov_b32 s8, 0x48000
	v_add_co_u32_e32 v44, vcc, s8, v152
	s_mov_b64 s[8:9], 0x50000
	v_cvt_pk_bf16_f32 v114, v104, v105
	v_or_b32_e32 v104, 16, v156
	v_addc_co_u32_e32 v45, vcc, 0, v153, vcc
	v_cvt_pk_bf16_f32 v34, v24, v25
	v_cvt_pk_bf16_f32 v35, v26, v27
	global_store_dwordx4 v[48:49], v[32:35], off offset:256 sc1
	v_ashrrev_i32_e32 v105, 31, v104
	v_cvt_pk_bf16_f32 v96, v96, v97
	v_cvt_pk_bf16_f32 v97, v98, v99
	v_cvt_pk_bf16_f32 v98, v88, v89
	v_or_b32_e32 v88, 32, v156
	v_lshl_add_u64 v[32:33], v[152:153], 0, s[8:9]
	s_mov_b32 s8, 0x50000
	v_cvt_pk_bf16_f32 v26, v28, v29
	v_add_co_u32_e32 v28, vcc, s8, v152
	v_cvt_pk_bf16_f32 v16, v16, v17
	v_cvt_pk_bf16_f32 v17, v18, v19
	s_mov_b64 s[8:9], 0x58000
	v_lshlrev_b64 v[104:105], 11, v[104:105]
	v_ashrrev_i32_e32 v89, 31, v88
	v_cvt_pk_bf16_f32 v80, v80, v81
	v_cvt_pk_bf16_f32 v81, v82, v83
	v_cvt_pk_bf16_f32 v82, v72, v73
	v_or_b32_e32 v72, 48, v156
	v_addc_co_u32_e32 v29, vcc, 0, v153, vcc
	v_cvt_pk_bf16_f32 v18, v8, v9
	v_cvt_pk_bf16_f32 v19, v10, v11
	global_store_dwordx4 v[32:33], v[16:19], off offset:256 sc1
	v_cvt_pk_bf16_f32 v115, v106, v107
	global_store_dwordx4 v[152:153], v[112:115], off offset:256 sc1
	v_lshlrev_b64 v[88:89], 11, v[88:89]
	v_lshl_add_u64 v[16:17], v[152:153], 0, s[8:9]
	s_mov_b32 s8, 0x58000
	v_lshl_add_u64 v[112:113], v[158:159], 0, v[104:105]
	v_ashrrev_i32_e32 v73, 31, v72
	v_cvt_pk_bf16_f32 v10, v12, v13
	v_add_co_u32_e32 v12, vcc, s8, v152
	v_cvt_pk_bf16_f32 v99, v90, v91
	global_store_dwordx4 v[112:113], v[96:99], off offset:256 sc1
	v_lshlrev_b64 v[72:73], 11, v[72:73]
	v_addc_co_u32_e32 v13, vcc, 0, v153, vcc
	v_lshl_add_u64 v[96:97], v[158:159], 0, v[88:89]
	v_cvt_pk_bf16_f32 v83, v74, v75
	global_store_dwordx4 v[96:97], v[80:83], off offset:256 sc1
	s_and_b64 vcc, exec, s[4:5]
	s_mov_b32 s37, s34
	v_lshl_add_u64 v[80:81], v[158:159], 0, v[72:73]
	s_mov_b32 s36, s35
	s_mov_b64 s[10:11], s[6:7]
	s_mov_b64 s[12:13], s[2:3]
	v_cvt_pk_bf16_f32 v124, v124, v125
	v_cvt_pk_bf16_f32 v125, v126, v127
	v_cvt_pk_bf16_f32 v126, v120, v121
	v_cvt_pk_bf16_f32 v127, v122, v123
	global_store_dwordx4 v[152:153], v[124:127], off sc1
	v_cvt_pk_bf16_f32 v104, v116, v117
	v_cvt_pk_bf16_f32 v105, v118, v119
	v_cvt_pk_bf16_f32 v106, v108, v109
	v_cvt_pk_bf16_f32 v107, v110, v111
	global_store_dwordx4 v[112:113], v[104:107], off sc1
	v_cvt_pk_bf16_f32 v88, v100, v101
	v_cvt_pk_bf16_f32 v89, v102, v103
	v_cvt_pk_bf16_f32 v90, v92, v93
	v_cvt_pk_bf16_f32 v91, v94, v95
	global_store_dwordx4 v[96:97], v[88:91], off sc1
	v_cvt_pk_bf16_f32 v72, v84, v85
	v_cvt_pk_bf16_f32 v73, v86, v87
	v_cvt_pk_bf16_f32 v74, v76, v77
	v_cvt_pk_bf16_f32 v75, v78, v79
	global_store_dwordx4 v[80:81], v[72:75], off sc1
	v_cvt_pk_bf16_f32 v71, v66, v67
	global_store_dwordx4 v[80:81], v[68:71], off offset:256 sc1
	v_cvt_pk_bf16_f32 v63, v58, v59
	global_store_dwordx4 v[56:57], v[60:63], off sc1
	v_cvt_pk_bf16_f32 v40, v52, v53
	v_cvt_pk_bf16_f32 v41, v54, v55
	v_cvt_pk_bf16_f32 v43, v46, v47
	global_store_dwordx4 v[44:45], v[40:43], off sc1
	v_cvt_pk_bf16_f32 v24, v36, v37
	v_cvt_pk_bf16_f32 v25, v38, v39
	v_cvt_pk_bf16_f32 v27, v30, v31
	global_store_dwordx4 v[28:29], v[24:27], off sc1
	v_cvt_pk_bf16_f32 v8, v20, v21
	v_cvt_pk_bf16_f32 v9, v22, v23
	v_cvt_pk_bf16_f32 v11, v14, v15
	global_store_dwordx4 v[12:13], v[8:11], off sc1
	v_cvt_pk_bf16_f32 v4, v4, v5
	v_cvt_pk_bf16_f32 v5, v6, v7
	v_cvt_pk_bf16_f32 v6, v0, v1
	v_cvt_pk_bf16_f32 v7, v2, v3
	global_store_dwordx4 v[16:17], v[4:7], off offset:256 sc1
	s_cbranch_vccz .LBB0_1223
	s_waitcnt vmcnt(0)
	s_cmpk_gt_u32 s14, 0xff
	s_cbranch_scc1 .LBB0_1238
	s_barrier
